# cache-policy hint: nt on the streaming f32 KV-cache loads of sample attention (132 loads)
# baseline (speedup 1.0000x reference)
; #define LAS __attribute__((address_space(3)))
; DI float bflo(unsigned w) { return __uint_as_float(w << 16); }
; DI float bfhi(unsigned w) { return __uint_as_float(w & 0xffff0000u); }
; DI float bf2f(bf16_t b) { return __uint_as_float((unsigned)b << 16); }
; #define LDS_WAIT() asm volatile("s_waitcnt lgkmcnt(0)" ::: "memory")
; DI void attn_sample_unit(const Params& p, int u, const bf16_t* Q, const bf16_t* Kb, const bf16_t* Vb, bf16_t* att, LAS float* sl, int lane) {
;     const int h = u & 15, t = (u >> 4) & 3, b = u >> 6;
;     const size_t qrow = (size_t)NP + b * 4 + t;
;     const float* ck = p.in[4]; const float* cv = p.in[5];
;     sl[lane] = bf2f(Q[qrow * 1024 + h * 64 + lane]);
;     LDS_WAIT();
;     float mx = -INFINITY;
; #pragma unroll 1
;     for (int e = 0; e < 9; ++e) { const int pat = e / 3, r = e - 3 * pat; const int dil = 1 << (2 * pat);
;         const int j = lane + 64 * r; const bool valid = j <= 128; const int idx = 2048 + t - dil * (valid ? j : 0);
;         float dot = 0.f;
;         if (idx >= 2048) { const bf16_t* kp = Kb + ((size_t)NP + b * 4 + (idx - 2048)) * 1024 + h * 64;
; #pragma unroll
;             for (int d8 = 0; d8 < 8; ++d8) { const u32x4 kw = *(const u32x4*)(kp + 8 * d8); const f32x4 q0 = *(const LAS f32x4*)(sl + 8 * d8), q1 = *(const LAS f32x4*)(sl + 8 * d8 + 4);
;                 dot += (bflo(kw.x) * q0[0] + bfhi(kw.x) * q0[1]) + (bflo(kw.y) * q0[2] + bfhi(kw.y) * q0[3]) + (bflo(kw.z) * q1[0] + bfhi(kw.z) * q1[1]) + (bflo(kw.w) * q1[2] + bfhi(kw.w) * q1[3]); } }
;         else { const float* kp = ck + (((size_t)b * 2048 + idx) * 16 + h) * 64;
; #pragma unroll
;             for (int d4 = 0; d4 < 16; ++d4) { const f32x4 kv = *(const f32x4*)(kp + 4 * d4); const f32x4 qv = *(const LAS f32x4*)(sl + 4 * d4); dot += (kv[0] * qv[0] + kv[1] * qv[1]) + (kv[2] * qv[2] + kv[3] * qv[3]); } }
.LBB0_1521:
	s_ashr_i32 s86, s80, 6
	s_lshl_b32 s0, s86, 2
	s_add_i32 s0, s0, 0x8000
	s_and_b32 s4, s80, 3
	s_ashr_i32 s1, s0, 31
	s_or_b32 s76, s0, s4
	s_mov_b32 s77, s1
	s_lshl_b64 s[78:79], s[76:77], 10
	s_bfe_u32 s5, s80, 0x40002
	v_writelane_b32 v254, s78, 12
	s_lshl_b32 s2, s5, 6
	s_lshl_b64 s[76:77], s[76:77], 11
	v_writelane_b32 v254, s79, 13
	v_writelane_b32 v254, s2, 10
	s_mov_b32 s90, s82
	v_readlane_b32 s78, v254, 6
	v_readlane_b32 s79, v254, 7
	s_add_u32 s2, s78, s76
	s_addc_u32 s77, s79, s77
	s_lshl_b32 s78, s5, 7
	s_add_u32 s76, s2, s78
	s_addc_u32 s77, s77, 0
	v_lshl_add_u64 v[0:1], v[128:129], 1, s[76:77]
	global_load_ushort v0, v[0:1], off
	s_or_b32 s2, s4, 0x800
	s_add_u32 s88, s96, s78
	s_addc_u32 s89, s97, 0
	s_ashr_i32 s87, s86, 31
	s_lshl_b32 s78, s5, 8
	s_lshl_b64 s[76:77], s[86:87], 23
	v_readlane_b32 s92, v254, 14
	v_readlane_b32 s93, v254, 15
	s_add_u32 s76, s92, s76
	s_addc_u32 s77, s93, s77
	v_readlane_b32 s94, v254, 16
	s_add_u32 s84, s76, s78
	s_addc_u32 s85, s77, 0
	v_mov_b32_e32 v40, 0xff800000
	v_mov_b32_e32 v41, v128
	v_mov_b32_e32 v42, v210
	s_mov_b32 s94, 0
	v_readlane_b32 s95, v254, 17
	s_waitcnt vmcnt(0)
	v_lshlrev_b32_e32 v0, 16, v0
	ds_write_b32 v145, v0
	s_waitcnt lgkmcnt(0)
	v_lshrrev_b32_e32 v41, 4, v128
	v_and_b32_e32 v42, 15, v128
	v_lshlrev_b32_e32 v43, 4, v42
	v_add_u32_e32 v51, s3, v43
	ds_read_b128 v[44:47], v51
	v_lshlrev_b32_e32 v48, 2, v41
	v_add_u32_e32 v48, s3, v48
	v_add_u32_e32 v48, 0x100, v48
	s_mov_b32 s100, 0x10001
	s_mov_b32 s101, 0x10001
	s_sub_i32 s1, 3, s4
	s_lshl_b32 s1, s1, 4
	s_lshr_b64 s[100:101], s[100:101], s1
	s_mov_b32 s98, 0x10001
	s_mov_b32 s99, 0x10001
	s_xor_b64 s[98:99], s[98:99], s[100:101]
	s_lshl_b32 s1, s0, 11
	s_add_u32 s94, s88, s1
	s_addc_u32 s95, s89, 0
	v_lshlrev_b32_e32 v102, 11, v41
	v_lshl_add_u32 v102, v42, 3, v102
	global_load_dwordx2 v[100:101], v102, s[94:95]
	s_waitcnt lgkmcnt(0)
	v_lshlrev_b32_e32 v49, 0, v41
	v_sub_u32_e32 v49, s2, v49
	v_min_i32_e32 v50, 0x7ff, v49
	v_lshl_add_u32 v49, v49, 12, v43
	v_lshl_add_u32 v50, v50, 12, v43
	s_mov_b64 s[76:77], s[84:85]
	global_load_dwordx4 v[0:3], v50, s[76:77] nt
	s_sub_u32 s76, s76, 0x4000
	s_subb_u32 s77, s77, 0
	global_load_dwordx4 v[4:7], v49, s[76:77] nt
	s_sub_u32 s76, s76, 0x4000
	s_subb_u32 s77, s77, 0
	global_load_dwordx4 v[8:11], v49, s[76:77] nt
	s_sub_u32 s76, s76, 0x4000
	s_subb_u32 s77, s77, 0
	global_load_dwordx4 v[12:15], v49, s[76:77] nt
	s_sub_u32 s76, s76, 0x4000
	s_subb_u32 s77, s77, 0
	global_load_dwordx4 v[16:19], v49, s[76:77] nt
	s_sub_u32 s76, s76, 0x4000
	s_subb_u32 s77, s77, 0
	global_load_dwordx4 v[20:23], v49, s[76:77] nt
	s_sub_u32 s76, s76, 0x4000
	s_subb_u32 s77, s77, 0
	global_load_dwordx4 v[24:27], v49, s[76:77] nt
	s_sub_u32 s76, s76, 0x4000
	s_subb_u32 s77, s77, 0
	global_load_dwordx4 v[28:31], v49, s[76:77] nt
	s_sub_u32 s76, s76, 0x4000
	s_subb_u32 s77, s77, 0
	global_load_dwordx4 v[32:35], v49, s[76:77] nt
	s_sub_u32 s76, s76, 0x4000
	s_subb_u32 s77, s77, 0
	global_load_dwordx4 v[36:39], v49, s[76:77] nt
	s_sub_u32 s76, s76, 0x4000
	s_subb_u32 s77, s77, 0
	global_load_dwordx4 v[52:55], v49, s[76:77] nt
	s_sub_u32 s76, s76, 0x4000
	s_subb_u32 s77, s77, 0
	global_load_dwordx4 v[56:59], v49, s[76:77] nt
	s_sub_u32 s76, s76, 0x4000
	s_subb_u32 s77, s77, 0
	global_load_dwordx4 v[60:63], v49, s[76:77] nt
	s_sub_u32 s76, s76, 0x4000
	s_subb_u32 s77, s77, 0
	global_load_dwordx4 v[64:67], v49, s[76:77] nt
	s_sub_u32 s76, s76, 0x4000
	s_subb_u32 s77, s77, 0
	global_load_dwordx4 v[68:71], v49, s[76:77] nt
	s_sub_u32 s76, s76, 0x4000
	s_subb_u32 s77, s77, 0
	global_load_dwordx4 v[72:75], v49, s[76:77] nt
	s_sub_u32 s76, s76, 0x4000
	s_subb_u32 s77, s77, 0
	global_load_dwordx4 v[76:79], v49, s[76:77] nt
	s_sub_u32 s76, s76, 0x4000
	s_subb_u32 s77, s77, 0
	global_load_dwordx4 v[80:83], v49, s[76:77] nt
	s_sub_u32 s76, s76, 0x4000
	s_subb_u32 s77, s77, 0
	global_load_dwordx4 v[84:87], v49, s[76:77] nt
	s_sub_u32 s76, s76, 0x4000
	s_subb_u32 s77, s77, 0
	global_load_dwordx4 v[88:91], v49, s[76:77] nt
	s_sub_u32 s76, s76, 0x4000
	s_subb_u32 s77, s77, 0
	global_load_dwordx4 v[92:95], v49, s[76:77] nt
	s_sub_u32 s76, s76, 0x4000
	s_subb_u32 s77, s77, 0
	global_load_dwordx4 v[96:99], v49, s[76:77] nt
	s_sub_u32 s76, s76, 0x4000
	s_subb_u32 s77, s77, 0
	s_waitcnt vmcnt(11)
; #define LAS __attribute__((address_space(3)))
; DI float bflo(unsigned w) { return __uint_as_float(w << 16); }
; DI float bfhi(unsigned w) { return __uint_as_float(w & 0xffff0000u); }
; DI void attn_sample_unit(const Params& p, int u, const bf16_t* Q, const bf16_t* Kb, const bf16_t* Vb, bf16_t* att, LAS float* sl, int lane) {
;     ...
;         if (idx >= 2048) { const bf16_t* kp = Kb + ((size_t)NP + b * 4 + (idx - 2048)) * 1024 + h * 64;
; #pragma unroll
;             for (int d8 = 0; d8 < 8; ++d8) { const u32x4 kw = *(const u32x4*)(kp + 8 * d8); const f32x4 q0 = *(const LAS f32x4*)(sl + 8 * d8), q1 = *(const LAS f32x4*)(sl + 8 * d8 + 4);
;                 dot += (bflo(kw.x) * q0[0] + bfhi(kw.x) * q0[1]) + (bflo(kw.y) * q0[2] + bfhi(kw.y) * q0[3]) + (bflo(kw.z) * q1[0] + bfhi(kw.z) * q1[1]) + (bflo(kw.w) * q1[2] + bfhi(kw.w) * q1[3]); } }
;         else { const float* kp = ck + (((size_t)b * 2048 + idx) * 16 + h) * 64;
; #pragma unroll
;             for (int d4 = 0; d4 < 16; ++d4) { const f32x4 kv = *(const f32x4*)(kp + 4 * d4); const f32x4 qv = *(const LAS f32x4*)(sl + 4 * d4); dot += (kv[0] * qv[0] + kv[1] * qv[1]) + (kv[2] * qv[2] + kv[3] * qv[3]); } }
;         if (valid) { sl[64 + pat * 192 + j] = dot; mx = fmaxf(mx, dot); } }
	v_lshlrev_b32_e32 v104, 16, v100
	v_and_b32_e32 v105, 0xffff0000, v100
	v_lshlrev_b32_e32 v106, 16, v101
	v_and_b32_e32 v107, 0xffff0000, v101
	v_mul_f32_e32 v104, v104, v44
	v_fmac_f32_e32 v104, v105, v45
	v_fmac_f32_e32 v104, v106, v46
	v_fmac_f32_e32 v104, v107, v47
	s_nop 1
	v_add_f32_dpp v104, v104, v104 quad_perm:[1,0,3,2] row_mask:0xf bank_mask:0xf
	s_nop 1
	v_add_f32_dpp v104, v104, v104 quad_perm:[2,3,0,1] row_mask:0xf bank_mask:0xf
	s_nop 1
	v_add_f32_dpp v104, v104, v104 row_half_mirror row_mask:0xf bank_mask:0xf
	s_nop 1
	v_add_f32_dpp v104, v104, v104 row_mirror row_mask:0xf bank_mask:0xf
	s_lshl_b32 s1, s4, 2
	s_add_i32 s1, s1, s3
	s_addk_i32 s1, 0x100
	v_lshlrev_b32_e32 v108, 2, v41
	v_sub_u32_e32 v108, s1, v108
	v_mov_b32_e32 v109, s3
	s_mov_b64 exec, s[100:101]
	ds_write_b32 v108, v104
	v_max_f32_e32 v40, v40, v104
	s_lshl_b32 s1, s4, 4
	s_lshl_b64 s[82:83], 1, s1
	s_mov_b64 exec, s[82:83]
	ds_write_b32 v109, v104 offset:1024
	ds_write_b32 v109, v104 offset:1792
	s_mov_b64 exec, -1
	s_nop 4
	v_mul_f32_e32 v0, v0, v44
	v_mul_f32_e32 v4, v4, v44
	v_mul_f32_e32 v8, v8, v44
	v_mul_f32_e32 v12, v12, v44
	v_mul_f32_e32 v16, v16, v44
	v_mul_f32_e32 v20, v20, v44
	v_mul_f32_e32 v24, v24, v44
	v_mul_f32_e32 v28, v28, v44
	v_mul_f32_e32 v32, v32, v44
	v_mul_f32_e32 v36, v36, v44
	v_mul_f32_e32 v52, v52, v44
	v_fmac_f32_e32 v0, v1, v45
	v_fmac_f32_e32 v4, v5, v45
	v_fmac_f32_e32 v8, v9, v45
	v_fmac_f32_e32 v12, v13, v45
	v_fmac_f32_e32 v16, v17, v45
	v_fmac_f32_e32 v20, v21, v45
	v_fmac_f32_e32 v24, v25, v45
	v_fmac_f32_e32 v28, v29, v45
	v_fmac_f32_e32 v32, v33, v45
	v_fmac_f32_e32 v36, v37, v45
	v_fmac_f32_e32 v52, v53, v45
	v_fmac_f32_e32 v0, v2, v46
	v_fmac_f32_e32 v4, v6, v46
	v_fmac_f32_e32 v8, v10, v46
	v_fmac_f32_e32 v12, v14, v46
	v_fmac_f32_e32 v16, v18, v46
	v_fmac_f32_e32 v20, v22, v46
	v_fmac_f32_e32 v24, v26, v46
	v_fmac_f32_e32 v28, v30, v46
	v_fmac_f32_e32 v32, v34, v46
	v_fmac_f32_e32 v36, v38, v46
	v_fmac_f32_e32 v52, v54, v46
	v_fmac_f32_e32 v0, v3, v47
	v_fmac_f32_e32 v4, v7, v47
	v_fmac_f32_e32 v8, v11, v47
	v_fmac_f32_e32 v12, v15, v47
	v_fmac_f32_e32 v16, v19, v47
	v_fmac_f32_e32 v20, v23, v47
	v_fmac_f32_e32 v24, v27, v47
	v_fmac_f32_e32 v28, v31, v47
	v_fmac_f32_e32 v32, v35, v47
	v_fmac_f32_e32 v36, v39, v47
	v_fmac_f32_e32 v52, v55, v47
	s_nop 1
	v_add_f32_dpp v0, v0, v0 quad_perm:[1,0,3,2] row_mask:0xf bank_mask:0xf
	v_add_f32_dpp v4, v4, v4 quad_perm:[1,0,3,2] row_mask:0xf bank_mask:0xf
	v_add_f32_dpp v8, v8, v8 quad_perm:[1,0,3,2] row_mask:0xf bank_mask:0xf
	v_add_f32_dpp v12, v12, v12 quad_perm:[1,0,3,2] row_mask:0xf bank_mask:0xf
	v_add_f32_dpp v16, v16, v16 quad_perm:[1,0,3,2] row_mask:0xf bank_mask:0xf
	v_add_f32_dpp v20, v20, v20 quad_perm:[1,0,3,2] row_mask:0xf bank_mask:0xf
	v_add_f32_dpp v24, v24, v24 quad_perm:[1,0,3,2] row_mask:0xf bank_mask:0xf
	v_add_f32_dpp v28, v28, v28 quad_perm:[1,0,3,2] row_mask:0xf bank_mask:0xf
	v_add_f32_dpp v32, v32, v32 quad_perm:[1,0,3,2] row_mask:0xf bank_mask:0xf
	v_add_f32_dpp v36, v36, v36 quad_perm:[1,0,3,2] row_mask:0xf bank_mask:0xf
	v_add_f32_dpp v52, v52, v52 quad_perm:[1,0,3,2] row_mask:0xf bank_mask:0xf
	s_nop 1
	v_add_f32_dpp v0, v0, v0 quad_perm:[2,3,0,1] row_mask:0xf bank_mask:0xf
	v_add_f32_dpp v4, v4, v4 quad_perm:[2,3,0,1] row_mask:0xf bank_mask:0xf
	v_add_f32_dpp v8, v8, v8 quad_perm:[2,3,0,1] row_mask:0xf bank_mask:0xf
	v_add_f32_dpp v12, v12, v12 quad_perm:[2,3,0,1] row_mask:0xf bank_mask:0xf
	v_add_f32_dpp v16, v16, v16 quad_perm:[2,3,0,1] row_mask:0xf bank_mask:0xf
	v_add_f32_dpp v20, v20, v20 quad_perm:[2,3,0,1] row_mask:0xf bank_mask:0xf
	v_add_f32_dpp v24, v24, v24 quad_perm:[2,3,0,1] row_mask:0xf bank_mask:0xf
	v_add_f32_dpp v28, v28, v28 quad_perm:[2,3,0,1] row_mask:0xf bank_mask:0xf
	v_add_f32_dpp v32, v32, v32 quad_perm:[2,3,0,1] row_mask:0xf bank_mask:0xf
	v_add_f32_dpp v36, v36, v36 quad_perm:[2,3,0,1] row_mask:0xf bank_mask:0xf
	v_add_f32_dpp v52, v52, v52 quad_perm:[2,3,0,1] row_mask:0xf bank_mask:0xf
	s_nop 1
	v_add_f32_dpp v0, v0, v0 row_half_mirror row_mask:0xf bank_mask:0xf
	v_add_f32_dpp v4, v4, v4 row_half_mirror row_mask:0xf bank_mask:0xf
	v_add_f32_dpp v8, v8, v8 row_half_mirror row_mask:0xf bank_mask:0xf
	v_add_f32_dpp v12, v12, v12 row_half_mirror row_mask:0xf bank_mask:0xf
	v_add_f32_dpp v16, v16, v16 row_half_mirror row_mask:0xf bank_mask:0xf
	v_add_f32_dpp v20, v20, v20 row_half_mirror row_mask:0xf bank_mask:0xf
	v_add_f32_dpp v24, v24, v24 row_half_mirror row_mask:0xf bank_mask:0xf
	v_add_f32_dpp v28, v28, v28 row_half_mirror row_mask:0xf bank_mask:0xf
	v_add_f32_dpp v32, v32, v32 row_half_mirror row_mask:0xf bank_mask:0xf
	v_add_f32_dpp v36, v36, v36 row_half_mirror row_mask:0xf bank_mask:0xf
	v_add_f32_dpp v52, v52, v52 row_half_mirror row_mask:0xf bank_mask:0xf
	s_nop 1
	v_add_f32_dpp v0, v0, v0 row_mirror row_mask:0xf bank_mask:0xf
	v_add_f32_dpp v4, v4, v4 row_mirror row_mask:0xf bank_mask:0xf
	v_add_f32_dpp v8, v8, v8 row_mirror row_mask:0xf bank_mask:0xf
	v_add_f32_dpp v12, v12, v12 row_mirror row_mask:0xf bank_mask:0xf
	v_add_f32_dpp v16, v16, v16 row_mirror row_mask:0xf bank_mask:0xf
	v_add_f32_dpp v20, v20, v20 row_mirror row_mask:0xf bank_mask:0xf
	v_add_f32_dpp v24, v24, v24 row_mirror row_mask:0xf bank_mask:0xf
	v_add_f32_dpp v28, v28, v28 row_mirror row_mask:0xf bank_mask:0xf
	v_add_f32_dpp v32, v32, v32 row_mirror row_mask:0xf bank_mask:0xf
	v_add_f32_dpp v36, v36, v36 row_mirror row_mask:0xf bank_mask:0xf
	v_add_f32_dpp v52, v52, v52 row_mirror row_mask:0xf bank_mask:0xf
	s_nop 1
	s_mov_b64 exec, s[98:99]
	ds_write_b32 v48, v0 offset:0
	v_max_f32_e32 v40, v40, v0
	s_mov_b32 s82, 0x10001
; #define LAS __attribute__((address_space(3)))
; DI float bflo(unsigned w) { return __uint_as_float(w << 16); }
; DI float bfhi(unsigned w) { return __uint_as_float(w & 0xffff0000u); }
; DI void attn_sample_unit(const Params& p, int u, const bf16_t* Q, const bf16_t* Kb, const bf16_t* Vb, bf16_t* att, LAS float* sl, int lane) {
;     ...
;     for (int e = 0; e < 9; ++e) { const int pat = e / 3, r = e - 3 * pat; const int dil = 1 << (2 * pat);
;         const int j = lane + 64 * r; const bool valid = j <= 128; const int idx = 2048 + t - dil * (valid ? j : 0);
;         float dot = 0.f;
;         if (idx >= 2048) { const bf16_t* kp = Kb + ((size_t)NP + b * 4 + (idx - 2048)) * 1024 + h * 64;
; #pragma unroll
;             for (int d8 = 0; d8 < 8; ++d8) { const u32x4 kw = *(const u32x4*)(kp + 8 * d8); const f32x4 q0 = *(const LAS f32x4*)(sl + 8 * d8), q1 = *(const LAS f32x4*)(sl + 8 * d8 + 4);
;                 dot += (bflo(kw.x) * q0[0] + bfhi(kw.x) * q0[1]) + (bflo(kw.y) * q0[2] + bfhi(kw.y) * q0[3]) + (bflo(kw.z) * q1[0] + bfhi(kw.z) * q1[1]) + (bflo(kw.w) * q1[2] + bfhi(kw.w) * q1[3]); } }
;         else { const float* kp = ck + (((size_t)b * 2048 + idx) * 16 + h) * 64;
; #pragma unroll
;             for (int d4 = 0; d4 < 16; ++d4) { const f32x4 kv = *(const f32x4*)(kp + 4 * d4); const f32x4 qv = *(const LAS f32x4*)(sl + 4 * d4); dot += (kv[0] * qv[0] + kv[1] * qv[1]) + (kv[2] * qv[2] + kv[3] * qv[3]); } }
;         if (valid) { sl[64 + pat * 192 + j] = dot; mx = fmaxf(mx, dot); } }
	s_mov_b32 s83, 0x10001
	s_mov_b64 exec, s[82:83]
	ds_write_b32 v48, v4 offset:16
	v_max_f32_e32 v40, v40, v4
	ds_write_b32 v48, v8 offset:32
	v_max_f32_e32 v40, v40, v8
	ds_write_b32 v48, v12 offset:48
	v_max_f32_e32 v40, v40, v12
	ds_write_b32 v48, v16 offset:64
	v_max_f32_e32 v40, v40, v16
	ds_write_b32 v48, v20 offset:80
	v_max_f32_e32 v40, v40, v20
	ds_write_b32 v48, v24 offset:96
	v_max_f32_e32 v40, v40, v24
	ds_write_b32 v48, v28 offset:112
	v_max_f32_e32 v40, v40, v28
	ds_write_b32 v48, v32 offset:128
	v_max_f32_e32 v40, v40, v32
	ds_write_b32 v48, v36 offset:144
	v_max_f32_e32 v40, v40, v36
	ds_write_b32 v48, v52 offset:160
	v_max_f32_e32 v40, v40, v52
	s_mov_b64 exec, -1
	s_nop 4
	global_load_dwordx4 v[0:3], v49, s[76:77] nt
	s_sub_u32 s76, s76, 0x4000
	s_subb_u32 s77, s77, 0
	global_load_dwordx4 v[4:7], v49, s[76:77] nt
	s_sub_u32 s76, s76, 0x4000
	s_subb_u32 s77, s77, 0
	global_load_dwordx4 v[8:11], v49, s[76:77] nt
	s_sub_u32 s76, s76, 0x4000
	s_subb_u32 s77, s77, 0
	global_load_dwordx4 v[12:15], v49, s[76:77] nt
	s_sub_u32 s76, s76, 0x4000
	s_subb_u32 s77, s77, 0
	global_load_dwordx4 v[16:19], v49, s[76:77] nt
	s_sub_u32 s76, s76, 0x4000
	s_subb_u32 s77, s77, 0
	global_load_dwordx4 v[20:23], v49, s[76:77] nt
	s_sub_u32 s76, s76, 0x4000
	s_subb_u32 s77, s77, 0
	global_load_dwordx4 v[24:27], v49, s[76:77] nt
	s_sub_u32 s76, s76, 0x4000
	s_subb_u32 s77, s77, 0
	global_load_dwordx4 v[28:31], v49, s[76:77] nt
	s_sub_u32 s76, s76, 0x4000
	s_subb_u32 s77, s77, 0
	global_load_dwordx4 v[32:35], v49, s[76:77] nt
	s_sub_u32 s76, s76, 0x4000
	s_subb_u32 s77, s77, 0
	global_load_dwordx4 v[36:39], v49, s[76:77] nt
	s_sub_u32 s76, s76, 0x4000
	s_subb_u32 s77, s77, 0
	s_mov_b64 exec, 0xffff
	global_load_dwordx4 v[52:55], v49, s[76:77] nt
	s_mov_b64 exec, -1
	s_waitcnt vmcnt(11)
	v_mul_f32_e32 v56, v56, v44
	v_mul_f32_e32 v60, v60, v44
	v_mul_f32_e32 v64, v64, v44
	v_mul_f32_e32 v68, v68, v44
	v_mul_f32_e32 v72, v72, v44
	v_mul_f32_e32 v76, v76, v44
	v_mul_f32_e32 v80, v80, v44
	v_mul_f32_e32 v84, v84, v44
	v_mul_f32_e32 v88, v88, v44
	v_mul_f32_e32 v92, v92, v44
	v_mul_f32_e32 v96, v96, v44
	v_fmac_f32_e32 v56, v57, v45
	v_fmac_f32_e32 v60, v61, v45
	v_fmac_f32_e32 v64, v65, v45
	v_fmac_f32_e32 v68, v69, v45
	v_fmac_f32_e32 v72, v73, v45
	v_fmac_f32_e32 v76, v77, v45
	v_fmac_f32_e32 v80, v81, v45
	v_fmac_f32_e32 v84, v85, v45
	v_fmac_f32_e32 v88, v89, v45
	v_fmac_f32_e32 v92, v93, v45
	v_fmac_f32_e32 v96, v97, v45
	v_fmac_f32_e32 v56, v58, v46
	v_fmac_f32_e32 v60, v62, v46
	v_fmac_f32_e32 v64, v66, v46
	v_fmac_f32_e32 v68, v70, v46
	v_fmac_f32_e32 v72, v74, v46
	v_fmac_f32_e32 v76, v78, v46
	v_fmac_f32_e32 v80, v82, v46
	v_fmac_f32_e32 v84, v86, v46
	v_fmac_f32_e32 v88, v90, v46
	v_fmac_f32_e32 v92, v94, v46
	v_fmac_f32_e32 v96, v98, v46
	v_fmac_f32_e32 v56, v59, v47
	v_fmac_f32_e32 v60, v63, v47
	v_fmac_f32_e32 v64, v67, v47
	v_fmac_f32_e32 v68, v71, v47
	v_fmac_f32_e32 v72, v75, v47
	v_fmac_f32_e32 v76, v79, v47
	v_fmac_f32_e32 v80, v83, v47
	v_fmac_f32_e32 v84, v87, v47
	v_fmac_f32_e32 v88, v91, v47
	v_fmac_f32_e32 v92, v95, v47
	v_fmac_f32_e32 v96, v99, v47
	s_nop 1
	v_add_f32_dpp v56, v56, v56 quad_perm:[1,0,3,2] row_mask:0xf bank_mask:0xf
	v_add_f32_dpp v60, v60, v60 quad_perm:[1,0,3,2] row_mask:0xf bank_mask:0xf
	v_add_f32_dpp v64, v64, v64 quad_perm:[1,0,3,2] row_mask:0xf bank_mask:0xf
	v_add_f32_dpp v68, v68, v68 quad_perm:[1,0,3,2] row_mask:0xf bank_mask:0xf
	v_add_f32_dpp v72, v72, v72 quad_perm:[1,0,3,2] row_mask:0xf bank_mask:0xf
	v_add_f32_dpp v76, v76, v76 quad_perm:[1,0,3,2] row_mask:0xf bank_mask:0xf
	v_add_f32_dpp v80, v80, v80 quad_perm:[1,0,3,2] row_mask:0xf bank_mask:0xf
	v_add_f32_dpp v84, v84, v84 quad_perm:[1,0,3,2] row_mask:0xf bank_mask:0xf
	v_add_f32_dpp v88, v88, v88 quad_perm:[1,0,3,2] row_mask:0xf bank_mask:0xf
	v_add_f32_dpp v92, v92, v92 quad_perm:[1,0,3,2] row_mask:0xf bank_mask:0xf
	v_add_f32_dpp v96, v96, v96 quad_perm:[1,0,3,2] row_mask:0xf bank_mask:0xf
	s_nop 1
	v_add_f32_dpp v56, v56, v56 quad_perm:[2,3,0,1] row_mask:0xf bank_mask:0xf
	v_add_f32_dpp v60, v60, v60 quad_perm:[2,3,0,1] row_mask:0xf bank_mask:0xf
	v_add_f32_dpp v64, v64, v64 quad_perm:[2,3,0,1] row_mask:0xf bank_mask:0xf
	v_add_f32_dpp v68, v68, v68 quad_perm:[2,3,0,1] row_mask:0xf bank_mask:0xf
	v_add_f32_dpp v72, v72, v72 quad_perm:[2,3,0,1] row_mask:0xf bank_mask:0xf
	v_add_f32_dpp v76, v76, v76 quad_perm:[2,3,0,1] row_mask:0xf bank_mask:0xf
	v_add_f32_dpp v80, v80, v80 quad_perm:[2,3,0,1] row_mask:0xf bank_mask:0xf
	v_add_f32_dpp v84, v84, v84 quad_perm:[2,3,0,1] row_mask:0xf bank_mask:0xf
	v_add_f32_dpp v88, v88, v88 quad_perm:[2,3,0,1] row_mask:0xf bank_mask:0xf
	v_add_f32_dpp v92, v92, v92 quad_perm:[2,3,0,1] row_mask:0xf bank_mask:0xf
	v_add_f32_dpp v96, v96, v96 quad_perm:[2,3,0,1] row_mask:0xf bank_mask:0xf
	s_nop 1
	v_add_f32_dpp v56, v56, v56 row_half_mirror row_mask:0xf bank_mask:0xf
	v_add_f32_dpp v60, v60, v60 row_half_mirror row_mask:0xf bank_mask:0xf
	v_add_f32_dpp v64, v64, v64 row_half_mirror row_mask:0xf bank_mask:0xf
	v_add_f32_dpp v68, v68, v68 row_half_mirror row_mask:0xf bank_mask:0xf
	v_add_f32_dpp v72, v72, v72 row_half_mirror row_mask:0xf bank_mask:0xf
	v_add_f32_dpp v76, v76, v76 row_half_mirror row_mask:0xf bank_mask:0xf
	v_add_f32_dpp v80, v80, v80 row_half_mirror row_mask:0xf bank_mask:0xf
	v_add_f32_dpp v84, v84, v84 row_half_mirror row_mask:0xf bank_mask:0xf
	v_add_f32_dpp v88, v88, v88 row_half_mirror row_mask:0xf bank_mask:0xf
	v_add_f32_dpp v92, v92, v92 row_half_mirror row_mask:0xf bank_mask:0xf
	v_add_f32_dpp v96, v96, v96 row_half_mirror row_mask:0xf bank_mask:0xf
	s_nop 1
; #define LAS __attribute__((address_space(3)))
; DI float bflo(unsigned w) { return __uint_as_float(w << 16); }
; DI float bfhi(unsigned w) { return __uint_as_float(w & 0xffff0000u); }
; DI void attn_sample_unit(const Params& p, int u, const bf16_t* Q, const bf16_t* Kb, const bf16_t* Vb, bf16_t* att, LAS float* sl, int lane) {
;     ...
;     for (int e = 0; e < 9; ++e) { const int pat = e / 3, r = e - 3 * pat; const int dil = 1 << (2 * pat);
;         const int j = lane + 64 * r; const bool valid = j <= 128; const int idx = 2048 + t - dil * (valid ? j : 0);
;         float dot = 0.f;
;         if (idx >= 2048) { const bf16_t* kp = Kb + ((size_t)NP + b * 4 + (idx - 2048)) * 1024 + h * 64;
; #pragma unroll
;             for (int d8 = 0; d8 < 8; ++d8) { const u32x4 kw = *(const u32x4*)(kp + 8 * d8); const f32x4 q0 = *(const LAS f32x4*)(sl + 8 * d8), q1 = *(const LAS f32x4*)(sl + 8 * d8 + 4);
;                 dot += (bflo(kw.x) * q0[0] + bfhi(kw.x) * q0[1]) + (bflo(kw.y) * q0[2] + bfhi(kw.y) * q0[3]) + (bflo(kw.z) * q1[0] + bfhi(kw.z) * q1[1]) + (bflo(kw.w) * q1[2] + bfhi(kw.w) * q1[3]); } }
;         else { const float* kp = ck + (((size_t)b * 2048 + idx) * 16 + h) * 64;
; #pragma unroll
;             for (int d4 = 0; d4 < 16; ++d4) { const f32x4 kv = *(const f32x4*)(kp + 4 * d4); const f32x4 qv = *(const LAS f32x4*)(sl + 4 * d4); dot += (kv[0] * qv[0] + kv[1] * qv[1]) + (kv[2] * qv[2] + kv[3] * qv[3]); } }
;         if (valid) { sl[64 + pat * 192 + j] = dot; mx = fmaxf(mx, dot); } }
	v_add_f32_dpp v56, v56, v56 row_mirror row_mask:0xf bank_mask:0xf
	v_add_f32_dpp v60, v60, v60 row_mirror row_mask:0xf bank_mask:0xf
	v_add_f32_dpp v64, v64, v64 row_mirror row_mask:0xf bank_mask:0xf
	v_add_f32_dpp v68, v68, v68 row_mirror row_mask:0xf bank_mask:0xf
	v_add_f32_dpp v72, v72, v72 row_mirror row_mask:0xf bank_mask:0xf
	v_add_f32_dpp v76, v76, v76 row_mirror row_mask:0xf bank_mask:0xf
	v_add_f32_dpp v80, v80, v80 row_mirror row_mask:0xf bank_mask:0xf
	v_add_f32_dpp v84, v84, v84 row_mirror row_mask:0xf bank_mask:0xf
	v_add_f32_dpp v88, v88, v88 row_mirror row_mask:0xf bank_mask:0xf
	v_add_f32_dpp v92, v92, v92 row_mirror row_mask:0xf bank_mask:0xf
	v_add_f32_dpp v96, v96, v96 row_mirror row_mask:0xf bank_mask:0xf
	s_nop 1
	s_mov_b32 s82, 0x10001
	s_mov_b32 s83, 0x10001
	s_mov_b64 exec, s[82:83]
	ds_write_b32 v48, v56 offset:176
	v_max_f32_e32 v40, v40, v56
	ds_write_b32 v48, v60 offset:192
	v_max_f32_e32 v40, v40, v60
	ds_write_b32 v48, v64 offset:208
	v_max_f32_e32 v40, v40, v64
	ds_write_b32 v48, v68 offset:224
	v_max_f32_e32 v40, v40, v68
	ds_write_b32 v48, v72 offset:240
	v_max_f32_e32 v40, v40, v72
	ds_write_b32 v48, v76 offset:256
	v_max_f32_e32 v40, v40, v76
	ds_write_b32 v48, v80 offset:272
	v_max_f32_e32 v40, v40, v80
	ds_write_b32 v48, v84 offset:288
	v_max_f32_e32 v40, v40, v84
	ds_write_b32 v48, v88 offset:304
	v_max_f32_e32 v40, v40, v88
	ds_write_b32 v48, v92 offset:320
	v_max_f32_e32 v40, v40, v92
	ds_write_b32 v48, v96 offset:336
	v_max_f32_e32 v40, v40, v96
	s_mov_b64 exec, -1
	s_nop 4
	v_lshlrev_b32_e32 v49, 2, v41
	v_sub_u32_e32 v49, s2, v49
	v_min_i32_e32 v50, 0x7ff, v49
	v_lshl_add_u32 v49, v49, 12, v43
	v_lshl_add_u32 v50, v50, 12, v43
	s_mov_b64 s[76:77], s[84:85]
	global_load_dwordx4 v[56:59], v50, s[76:77] nt
	s_sub_u32 s76, s76, 0x10000
	s_subb_u32 s77, s77, 0
	global_load_dwordx4 v[60:63], v49, s[76:77] nt
	s_sub_u32 s76, s76, 0x10000
	s_subb_u32 s77, s77, 0
	global_load_dwordx4 v[64:67], v49, s[76:77] nt
	s_sub_u32 s76, s76, 0x10000
	s_subb_u32 s77, s77, 0
	global_load_dwordx4 v[68:71], v49, s[76:77] nt
	s_sub_u32 s76, s76, 0x10000
	s_subb_u32 s77, s77, 0
	global_load_dwordx4 v[72:75], v49, s[76:77] nt
	s_sub_u32 s76, s76, 0x10000
	s_subb_u32 s77, s77, 0
	global_load_dwordx4 v[76:79], v49, s[76:77] nt
	s_sub_u32 s76, s76, 0x10000
	s_subb_u32 s77, s77, 0
	global_load_dwordx4 v[80:83], v49, s[76:77] nt
	s_sub_u32 s76, s76, 0x10000
	s_subb_u32 s77, s77, 0
	global_load_dwordx4 v[84:87], v49, s[76:77] nt
	s_sub_u32 s76, s76, 0x10000
	s_subb_u32 s77, s77, 0
	global_load_dwordx4 v[88:91], v49, s[76:77] nt
	s_sub_u32 s76, s76, 0x10000
	s_subb_u32 s77, s77, 0
	global_load_dwordx4 v[92:95], v49, s[76:77] nt
	s_sub_u32 s76, s76, 0x10000
	s_subb_u32 s77, s77, 0
	global_load_dwordx4 v[96:99], v49, s[76:77] nt
	s_sub_u32 s76, s76, 0x10000
	s_subb_u32 s77, s77, 0
	s_waitcnt vmcnt(11)
	v_mul_f32_e32 v0, v0, v44
	v_mul_f32_e32 v4, v4, v44
	v_mul_f32_e32 v8, v8, v44
	v_mul_f32_e32 v12, v12, v44
	v_mul_f32_e32 v16, v16, v44
	v_mul_f32_e32 v20, v20, v44
	v_mul_f32_e32 v24, v24, v44
	v_mul_f32_e32 v28, v28, v44
	v_mul_f32_e32 v32, v32, v44
	v_mul_f32_e32 v36, v36, v44
	v_mul_f32_e32 v52, v52, v44
	v_fmac_f32_e32 v0, v1, v45
	v_fmac_f32_e32 v4, v5, v45
	v_fmac_f32_e32 v8, v9, v45
	v_fmac_f32_e32 v12, v13, v45
	v_fmac_f32_e32 v16, v17, v45
	v_fmac_f32_e32 v20, v21, v45
	v_fmac_f32_e32 v24, v25, v45
	v_fmac_f32_e32 v28, v29, v45
	v_fmac_f32_e32 v32, v33, v45
	v_fmac_f32_e32 v36, v37, v45
	v_fmac_f32_e32 v52, v53, v45
	v_fmac_f32_e32 v0, v2, v46
	v_fmac_f32_e32 v4, v6, v46
	v_fmac_f32_e32 v8, v10, v46
	v_fmac_f32_e32 v12, v14, v46
	v_fmac_f32_e32 v16, v18, v46
	v_fmac_f32_e32 v20, v22, v46
	v_fmac_f32_e32 v24, v26, v46
	v_fmac_f32_e32 v28, v30, v46
	v_fmac_f32_e32 v32, v34, v46
	v_fmac_f32_e32 v36, v38, v46
	v_fmac_f32_e32 v52, v54, v46
	v_fmac_f32_e32 v0, v3, v47
	v_fmac_f32_e32 v4, v7, v47
	v_fmac_f32_e32 v8, v11, v47
	v_fmac_f32_e32 v12, v15, v47
	v_fmac_f32_e32 v16, v19, v47
	v_fmac_f32_e32 v20, v23, v47
	v_fmac_f32_e32 v24, v27, v47
	v_fmac_f32_e32 v28, v31, v47
	v_fmac_f32_e32 v32, v35, v47
	v_fmac_f32_e32 v36, v39, v47
	v_fmac_f32_e32 v52, v55, v47
	s_nop 1
	v_add_f32_dpp v0, v0, v0 quad_perm:[1,0,3,2] row_mask:0xf bank_mask:0xf
	v_add_f32_dpp v4, v4, v4 quad_perm:[1,0,3,2] row_mask:0xf bank_mask:0xf
	v_add_f32_dpp v8, v8, v8 quad_perm:[1,0,3,2] row_mask:0xf bank_mask:0xf
	v_add_f32_dpp v12, v12, v12 quad_perm:[1,0,3,2] row_mask:0xf bank_mask:0xf
	v_add_f32_dpp v16, v16, v16 quad_perm:[1,0,3,2] row_mask:0xf bank_mask:0xf
	v_add_f32_dpp v20, v20, v20 quad_perm:[1,0,3,2] row_mask:0xf bank_mask:0xf
	v_add_f32_dpp v24, v24, v24 quad_perm:[1,0,3,2] row_mask:0xf bank_mask:0xf
	v_add_f32_dpp v28, v28, v28 quad_perm:[1,0,3,2] row_mask:0xf bank_mask:0xf
	v_add_f32_dpp v32, v32, v32 quad_perm:[1,0,3,2] row_mask:0xf bank_mask:0xf
	v_add_f32_dpp v36, v36, v36 quad_perm:[1,0,3,2] row_mask:0xf bank_mask:0xf
	v_add_f32_dpp v52, v52, v52 quad_perm:[1,0,3,2] row_mask:0xf bank_mask:0xf
	s_nop 1
	v_add_f32_dpp v0, v0, v0 quad_perm:[2,3,0,1] row_mask:0xf bank_mask:0xf
	v_add_f32_dpp v4, v4, v4 quad_perm:[2,3,0,1] row_mask:0xf bank_mask:0xf
	v_add_f32_dpp v8, v8, v8 quad_perm:[2,3,0,1] row_mask:0xf bank_mask:0xf
	v_add_f32_dpp v12, v12, v12 quad_perm:[2,3,0,1] row_mask:0xf bank_mask:0xf
	v_add_f32_dpp v16, v16, v16 quad_perm:[2,3,0,1] row_mask:0xf bank_mask:0xf
	v_add_f32_dpp v20, v20, v20 quad_perm:[2,3,0,1] row_mask:0xf bank_mask:0xf
	v_add_f32_dpp v24, v24, v24 quad_perm:[2,3,0,1] row_mask:0xf bank_mask:0xf
	v_add_f32_dpp v28, v28, v28 quad_perm:[2,3,0,1] row_mask:0xf bank_mask:0xf
	v_add_f32_dpp v32, v32, v32 quad_perm:[2,3,0,1] row_mask:0xf bank_mask:0xf
; #define LAS __attribute__((address_space(3)))
; DI float bflo(unsigned w) { return __uint_as_float(w << 16); }
; DI float bfhi(unsigned w) { return __uint_as_float(w & 0xffff0000u); }
; DI void attn_sample_unit(const Params& p, int u, const bf16_t* Q, const bf16_t* Kb, const bf16_t* Vb, bf16_t* att, LAS float* sl, int lane) {
;     ...
;     for (int e = 0; e < 9; ++e) { const int pat = e / 3, r = e - 3 * pat; const int dil = 1 << (2 * pat);
;         const int j = lane + 64 * r; const bool valid = j <= 128; const int idx = 2048 + t - dil * (valid ? j : 0);
;         float dot = 0.f;
;         if (idx >= 2048) { const bf16_t* kp = Kb + ((size_t)NP + b * 4 + (idx - 2048)) * 1024 + h * 64;
; #pragma unroll
;             for (int d8 = 0; d8 < 8; ++d8) { const u32x4 kw = *(const u32x4*)(kp + 8 * d8); const f32x4 q0 = *(const LAS f32x4*)(sl + 8 * d8), q1 = *(const LAS f32x4*)(sl + 8 * d8 + 4);
;                 dot += (bflo(kw.x) * q0[0] + bfhi(kw.x) * q0[1]) + (bflo(kw.y) * q0[2] + bfhi(kw.y) * q0[3]) + (bflo(kw.z) * q1[0] + bfhi(kw.z) * q1[1]) + (bflo(kw.w) * q1[2] + bfhi(kw.w) * q1[3]); } }
;         else { const float* kp = ck + (((size_t)b * 2048 + idx) * 16 + h) * 64;
; #pragma unroll
;             for (int d4 = 0; d4 < 16; ++d4) { const f32x4 kv = *(const f32x4*)(kp + 4 * d4); const f32x4 qv = *(const LAS f32x4*)(sl + 4 * d4); dot += (kv[0] * qv[0] + kv[1] * qv[1]) + (kv[2] * qv[2] + kv[3] * qv[3]); } }
;         if (valid) { sl[64 + pat * 192 + j] = dot; mx = fmaxf(mx, dot); } }
	v_add_f32_dpp v36, v36, v36 quad_perm:[2,3,0,1] row_mask:0xf bank_mask:0xf
	v_add_f32_dpp v52, v52, v52 quad_perm:[2,3,0,1] row_mask:0xf bank_mask:0xf
	s_nop 1
	v_add_f32_dpp v0, v0, v0 row_half_mirror row_mask:0xf bank_mask:0xf
	v_add_f32_dpp v4, v4, v4 row_half_mirror row_mask:0xf bank_mask:0xf
	v_add_f32_dpp v8, v8, v8 row_half_mirror row_mask:0xf bank_mask:0xf
	v_add_f32_dpp v12, v12, v12 row_half_mirror row_mask:0xf bank_mask:0xf
	v_add_f32_dpp v16, v16, v16 row_half_mirror row_mask:0xf bank_mask:0xf
	v_add_f32_dpp v20, v20, v20 row_half_mirror row_mask:0xf bank_mask:0xf
	v_add_f32_dpp v24, v24, v24 row_half_mirror row_mask:0xf bank_mask:0xf
	v_add_f32_dpp v28, v28, v28 row_half_mirror row_mask:0xf bank_mask:0xf
	v_add_f32_dpp v32, v32, v32 row_half_mirror row_mask:0xf bank_mask:0xf
	v_add_f32_dpp v36, v36, v36 row_half_mirror row_mask:0xf bank_mask:0xf
	v_add_f32_dpp v52, v52, v52 row_half_mirror row_mask:0xf bank_mask:0xf
	s_nop 1
	v_add_f32_dpp v0, v0, v0 row_mirror row_mask:0xf bank_mask:0xf
	v_add_f32_dpp v4, v4, v4 row_mirror row_mask:0xf bank_mask:0xf
	v_add_f32_dpp v8, v8, v8 row_mirror row_mask:0xf bank_mask:0xf
	v_add_f32_dpp v12, v12, v12 row_mirror row_mask:0xf bank_mask:0xf
	v_add_f32_dpp v16, v16, v16 row_mirror row_mask:0xf bank_mask:0xf
	v_add_f32_dpp v20, v20, v20 row_mirror row_mask:0xf bank_mask:0xf
	v_add_f32_dpp v24, v24, v24 row_mirror row_mask:0xf bank_mask:0xf
	v_add_f32_dpp v28, v28, v28 row_mirror row_mask:0xf bank_mask:0xf
	v_add_f32_dpp v32, v32, v32 row_mirror row_mask:0xf bank_mask:0xf
	v_add_f32_dpp v36, v36, v36 row_mirror row_mask:0xf bank_mask:0xf
	v_add_f32_dpp v52, v52, v52 row_mirror row_mask:0xf bank_mask:0xf
	s_nop 1
	s_mov_b32 s82, 0x10001
	s_mov_b32 s83, 0x10001
	s_mov_b64 exec, s[82:83]
	ds_write_b32 v48, v0 offset:352
	v_max_f32_e32 v40, v40, v0
	ds_write_b32 v48, v4 offset:368
	v_max_f32_e32 v40, v40, v4
	ds_write_b32 v48, v8 offset:384
	v_max_f32_e32 v40, v40, v8
	ds_write_b32 v48, v12 offset:400
	v_max_f32_e32 v40, v40, v12
	ds_write_b32 v48, v16 offset:416
	v_max_f32_e32 v40, v40, v16
	ds_write_b32 v48, v20 offset:432
	v_max_f32_e32 v40, v40, v20
	ds_write_b32 v48, v24 offset:448
	v_max_f32_e32 v40, v40, v24
	ds_write_b32 v48, v28 offset:464
	v_max_f32_e32 v40, v40, v28
	ds_write_b32 v48, v32 offset:480
	v_max_f32_e32 v40, v40, v32
	ds_write_b32 v48, v36 offset:496
	v_max_f32_e32 v40, v40, v36
	s_mov_b64 exec, 1
	ds_write_b32 v48, v52 offset:512
	v_max_f32_e32 v40, v40, v52
	s_mov_b64 exec, -1
	s_nop 4
	global_load_dwordx4 v[0:3], v49, s[76:77] nt
	s_sub_u32 s76, s76, 0x10000
	s_subb_u32 s77, s77, 0
	global_load_dwordx4 v[4:7], v49, s[76:77] nt
	s_sub_u32 s76, s76, 0x10000
	s_subb_u32 s77, s77, 0
	global_load_dwordx4 v[8:11], v49, s[76:77] nt
	s_sub_u32 s76, s76, 0x10000
	s_subb_u32 s77, s77, 0
	global_load_dwordx4 v[12:15], v49, s[76:77] nt
	s_sub_u32 s76, s76, 0x10000
	s_subb_u32 s77, s77, 0
	global_load_dwordx4 v[16:19], v49, s[76:77] nt
	s_sub_u32 s76, s76, 0x10000
	s_subb_u32 s77, s77, 0
	global_load_dwordx4 v[20:23], v49, s[76:77] nt
	s_sub_u32 s76, s76, 0x10000
	s_subb_u32 s77, s77, 0
	global_load_dwordx4 v[24:27], v49, s[76:77] nt
	s_sub_u32 s76, s76, 0x10000
	s_subb_u32 s77, s77, 0
	global_load_dwordx4 v[28:31], v49, s[76:77] nt
	s_sub_u32 s76, s76, 0x10000
	s_subb_u32 s77, s77, 0
	global_load_dwordx4 v[32:35], v49, s[76:77] nt
	s_sub_u32 s76, s76, 0x10000
	s_subb_u32 s77, s77, 0
	global_load_dwordx4 v[36:39], v49, s[76:77] nt
	s_sub_u32 s76, s76, 0x10000
	s_subb_u32 s77, s77, 0
	global_load_dwordx4 v[52:55], v49, s[76:77] nt
	s_sub_u32 s76, s76, 0x10000
	s_subb_u32 s77, s77, 0
	s_waitcnt vmcnt(11)
	v_mul_f32_e32 v56, v56, v44
	v_mul_f32_e32 v60, v60, v44
	v_mul_f32_e32 v64, v64, v44
	v_mul_f32_e32 v68, v68, v44
	v_mul_f32_e32 v72, v72, v44
	v_mul_f32_e32 v76, v76, v44
	v_mul_f32_e32 v80, v80, v44
	v_mul_f32_e32 v84, v84, v44
	v_mul_f32_e32 v88, v88, v44
	v_mul_f32_e32 v92, v92, v44
	v_mul_f32_e32 v96, v96, v44
	v_fmac_f32_e32 v56, v57, v45
	v_fmac_f32_e32 v60, v61, v45
	v_fmac_f32_e32 v64, v65, v45
	v_fmac_f32_e32 v68, v69, v45
	v_fmac_f32_e32 v72, v73, v45
	v_fmac_f32_e32 v76, v77, v45
	v_fmac_f32_e32 v80, v81, v45
	v_fmac_f32_e32 v84, v85, v45
	v_fmac_f32_e32 v88, v89, v45
	v_fmac_f32_e32 v92, v93, v45
	v_fmac_f32_e32 v96, v97, v45
	v_fmac_f32_e32 v56, v58, v46
	v_fmac_f32_e32 v60, v62, v46
	v_fmac_f32_e32 v64, v66, v46
	v_fmac_f32_e32 v68, v70, v46
	v_fmac_f32_e32 v72, v74, v46
	v_fmac_f32_e32 v76, v78, v46
	v_fmac_f32_e32 v80, v82, v46
	v_fmac_f32_e32 v84, v86, v46
	v_fmac_f32_e32 v88, v90, v46
	v_fmac_f32_e32 v92, v94, v46
	v_fmac_f32_e32 v96, v98, v46
	v_fmac_f32_e32 v56, v59, v47
	v_fmac_f32_e32 v60, v63, v47
	v_fmac_f32_e32 v64, v67, v47
	v_fmac_f32_e32 v68, v71, v47
	v_fmac_f32_e32 v72, v75, v47
	v_fmac_f32_e32 v76, v79, v47
	v_fmac_f32_e32 v80, v83, v47
	v_fmac_f32_e32 v84, v87, v47
	v_fmac_f32_e32 v88, v91, v47
	v_fmac_f32_e32 v92, v95, v47
	v_fmac_f32_e32 v96, v99, v47
	s_nop 1
	v_add_f32_dpp v56, v56, v56 quad_perm:[1,0,3,2] row_mask:0xf bank_mask:0xf
	v_add_f32_dpp v60, v60, v60 quad_perm:[1,0,3,2] row_mask:0xf bank_mask:0xf
	v_add_f32_dpp v64, v64, v64 quad_perm:[1,0,3,2] row_mask:0xf bank_mask:0xf
	v_add_f32_dpp v68, v68, v68 quad_perm:[1,0,3,2] row_mask:0xf bank_mask:0xf
	v_add_f32_dpp v72, v72, v72 quad_perm:[1,0,3,2] row_mask:0xf bank_mask:0xf
	v_add_f32_dpp v76, v76, v76 quad_perm:[1,0,3,2] row_mask:0xf bank_mask:0xf
	v_add_f32_dpp v80, v80, v80 quad_perm:[1,0,3,2] row_mask:0xf bank_mask:0xf
	v_add_f32_dpp v84, v84, v84 quad_perm:[1,0,3,2] row_mask:0xf bank_mask:0xf
	v_add_f32_dpp v88, v88, v88 quad_perm:[1,0,3,2] row_mask:0xf bank_mask:0xf
; #define LAS __attribute__((address_space(3)))
; DI float bflo(unsigned w) { return __uint_as_float(w << 16); }
; DI float bfhi(unsigned w) { return __uint_as_float(w & 0xffff0000u); }
; DI void attn_sample_unit(const Params& p, int u, const bf16_t* Q, const bf16_t* Kb, const bf16_t* Vb, bf16_t* att, LAS float* sl, int lane) {
;     ...
;     for (int e = 0; e < 9; ++e) { const int pat = e / 3, r = e - 3 * pat; const int dil = 1 << (2 * pat);
;         const int j = lane + 64 * r; const bool valid = j <= 128; const int idx = 2048 + t - dil * (valid ? j : 0);
;         float dot = 0.f;
;         if (idx >= 2048) { const bf16_t* kp = Kb + ((size_t)NP + b * 4 + (idx - 2048)) * 1024 + h * 64;
; #pragma unroll
;             for (int d8 = 0; d8 < 8; ++d8) { const u32x4 kw = *(const u32x4*)(kp + 8 * d8); const f32x4 q0 = *(const LAS f32x4*)(sl + 8 * d8), q1 = *(const LAS f32x4*)(sl + 8 * d8 + 4);
;                 dot += (bflo(kw.x) * q0[0] + bfhi(kw.x) * q0[1]) + (bflo(kw.y) * q0[2] + bfhi(kw.y) * q0[3]) + (bflo(kw.z) * q1[0] + bfhi(kw.z) * q1[1]) + (bflo(kw.w) * q1[2] + bfhi(kw.w) * q1[3]); } }
;         else { const float* kp = ck + (((size_t)b * 2048 + idx) * 16 + h) * 64;
; #pragma unroll
;             for (int d4 = 0; d4 < 16; ++d4) { const f32x4 kv = *(const f32x4*)(kp + 4 * d4); const f32x4 qv = *(const LAS f32x4*)(sl + 4 * d4); dot += (kv[0] * qv[0] + kv[1] * qv[1]) + (kv[2] * qv[2] + kv[3] * qv[3]); } }
;         if (valid) { sl[64 + pat * 192 + j] = dot; mx = fmaxf(mx, dot); } }
	v_add_f32_dpp v92, v92, v92 quad_perm:[1,0,3,2] row_mask:0xf bank_mask:0xf
	v_add_f32_dpp v96, v96, v96 quad_perm:[1,0,3,2] row_mask:0xf bank_mask:0xf
	s_nop 1
	v_add_f32_dpp v56, v56, v56 quad_perm:[2,3,0,1] row_mask:0xf bank_mask:0xf
	v_add_f32_dpp v60, v60, v60 quad_perm:[2,3,0,1] row_mask:0xf bank_mask:0xf
	v_add_f32_dpp v64, v64, v64 quad_perm:[2,3,0,1] row_mask:0xf bank_mask:0xf
	v_add_f32_dpp v68, v68, v68 quad_perm:[2,3,0,1] row_mask:0xf bank_mask:0xf
	v_add_f32_dpp v72, v72, v72 quad_perm:[2,3,0,1] row_mask:0xf bank_mask:0xf
	v_add_f32_dpp v76, v76, v76 quad_perm:[2,3,0,1] row_mask:0xf bank_mask:0xf
	v_add_f32_dpp v80, v80, v80 quad_perm:[2,3,0,1] row_mask:0xf bank_mask:0xf
	v_add_f32_dpp v84, v84, v84 quad_perm:[2,3,0,1] row_mask:0xf bank_mask:0xf
	v_add_f32_dpp v88, v88, v88 quad_perm:[2,3,0,1] row_mask:0xf bank_mask:0xf
	v_add_f32_dpp v92, v92, v92 quad_perm:[2,3,0,1] row_mask:0xf bank_mask:0xf
	v_add_f32_dpp v96, v96, v96 quad_perm:[2,3,0,1] row_mask:0xf bank_mask:0xf
	s_nop 1
	v_add_f32_dpp v56, v56, v56 row_half_mirror row_mask:0xf bank_mask:0xf
	v_add_f32_dpp v60, v60, v60 row_half_mirror row_mask:0xf bank_mask:0xf
	v_add_f32_dpp v64, v64, v64 row_half_mirror row_mask:0xf bank_mask:0xf
	v_add_f32_dpp v68, v68, v68 row_half_mirror row_mask:0xf bank_mask:0xf
	v_add_f32_dpp v72, v72, v72 row_half_mirror row_mask:0xf bank_mask:0xf
	v_add_f32_dpp v76, v76, v76 row_half_mirror row_mask:0xf bank_mask:0xf
	v_add_f32_dpp v80, v80, v80 row_half_mirror row_mask:0xf bank_mask:0xf
	v_add_f32_dpp v84, v84, v84 row_half_mirror row_mask:0xf bank_mask:0xf
	v_add_f32_dpp v88, v88, v88 row_half_mirror row_mask:0xf bank_mask:0xf
	v_add_f32_dpp v92, v92, v92 row_half_mirror row_mask:0xf bank_mask:0xf
	v_add_f32_dpp v96, v96, v96 row_half_mirror row_mask:0xf bank_mask:0xf
	s_nop 1
	v_add_f32_dpp v56, v56, v56 row_mirror row_mask:0xf bank_mask:0xf
	v_add_f32_dpp v60, v60, v60 row_mirror row_mask:0xf bank_mask:0xf
	v_add_f32_dpp v64, v64, v64 row_mirror row_mask:0xf bank_mask:0xf
	v_add_f32_dpp v68, v68, v68 row_mirror row_mask:0xf bank_mask:0xf
	v_add_f32_dpp v72, v72, v72 row_mirror row_mask:0xf bank_mask:0xf
	v_add_f32_dpp v76, v76, v76 row_mirror row_mask:0xf bank_mask:0xf
	v_add_f32_dpp v80, v80, v80 row_mirror row_mask:0xf bank_mask:0xf
	v_add_f32_dpp v84, v84, v84 row_mirror row_mask:0xf bank_mask:0xf
	v_add_f32_dpp v88, v88, v88 row_mirror row_mask:0xf bank_mask:0xf
	v_add_f32_dpp v92, v92, v92 row_mirror row_mask:0xf bank_mask:0xf
	v_add_f32_dpp v96, v96, v96 row_mirror row_mask:0xf bank_mask:0xf
	s_nop 1
	s_mov_b32 s82, 0x10000
	s_mov_b32 s83, 0x10001
	s_mov_b64 exec, s[82:83]
	ds_write_b32 v48, v56 offset:768
	v_max_f32_e32 v40, v40, v56
	s_mov_b32 s82, 0x10001
	s_mov_b32 s83, 0x10001
	s_mov_b64 exec, s[82:83]
	ds_write_b32 v48, v60 offset:784
	v_max_f32_e32 v40, v40, v60
	ds_write_b32 v48, v64 offset:800
	v_max_f32_e32 v40, v40, v64
	ds_write_b32 v48, v68 offset:816
	v_max_f32_e32 v40, v40, v68
	ds_write_b32 v48, v72 offset:832
	v_max_f32_e32 v40, v40, v72
	ds_write_b32 v48, v76 offset:848
	v_max_f32_e32 v40, v40, v76
	ds_write_b32 v48, v80 offset:864
	v_max_f32_e32 v40, v40, v80
	ds_write_b32 v48, v84 offset:880
	v_max_f32_e32 v40, v40, v84
	ds_write_b32 v48, v88 offset:896
	v_max_f32_e32 v40, v40, v88
	ds_write_b32 v48, v92 offset:912
	v_max_f32_e32 v40, v40, v92
	ds_write_b32 v48, v96 offset:928
	v_max_f32_e32 v40, v40, v96
	s_mov_b64 exec, -1
	s_nop 4
	global_load_dwordx4 v[56:59], v49, s[76:77] nt
	s_sub_u32 s76, s76, 0x10000
	s_subb_u32 s77, s77, 0
	global_load_dwordx4 v[60:63], v49, s[76:77] nt
	s_sub_u32 s76, s76, 0x10000
	s_subb_u32 s77, s77, 0
	global_load_dwordx4 v[64:67], v49, s[76:77] nt
	s_sub_u32 s76, s76, 0x10000
	s_subb_u32 s77, s77, 0
	global_load_dwordx4 v[68:71], v49, s[76:77] nt
	s_sub_u32 s76, s76, 0x10000
	s_subb_u32 s77, s77, 0
	global_load_dwordx4 v[72:75], v49, s[76:77] nt
	s_sub_u32 s76, s76, 0x10000
	s_subb_u32 s77, s77, 0
	global_load_dwordx4 v[76:79], v49, s[76:77] nt
	s_sub_u32 s76, s76, 0x10000
	s_subb_u32 s77, s77, 0
	global_load_dwordx4 v[80:83], v49, s[76:77] nt
	s_sub_u32 s76, s76, 0x10000
	s_subb_u32 s77, s77, 0
	global_load_dwordx4 v[84:87], v49, s[76:77] nt
	s_sub_u32 s76, s76, 0x10000
	s_subb_u32 s77, s77, 0
	global_load_dwordx4 v[88:91], v49, s[76:77] nt
	s_sub_u32 s76, s76, 0x10000
	s_subb_u32 s77, s77, 0
	global_load_dwordx4 v[92:95], v49, s[76:77] nt
	s_sub_u32 s76, s76, 0x10000
	s_subb_u32 s77, s77, 0
	s_mov_b64 exec, 0xffff
	global_load_dwordx4 v[96:99], v49, s[76:77] nt
	s_mov_b64 exec, -1
	s_waitcnt vmcnt(11)
; #define LAS __attribute__((address_space(3)))
; DI float bflo(unsigned w) { return __uint_as_float(w << 16); }
; DI float bfhi(unsigned w) { return __uint_as_float(w & 0xffff0000u); }
; DI void attn_sample_unit(const Params& p, int u, const bf16_t* Q, const bf16_t* Kb, const bf16_t* Vb, bf16_t* att, LAS float* sl, int lane) {
;     ...
;     for (int e = 0; e < 9; ++e) { const int pat = e / 3, r = e - 3 * pat; const int dil = 1 << (2 * pat);
;         const int j = lane + 64 * r; const bool valid = j <= 128; const int idx = 2048 + t - dil * (valid ? j : 0);
;         float dot = 0.f;
;         if (idx >= 2048) { const bf16_t* kp = Kb + ((size_t)NP + b * 4 + (idx - 2048)) * 1024 + h * 64;
; #pragma unroll
;             for (int d8 = 0; d8 < 8; ++d8) { const u32x4 kw = *(const u32x4*)(kp + 8 * d8); const f32x4 q0 = *(const LAS f32x4*)(sl + 8 * d8), q1 = *(const LAS f32x4*)(sl + 8 * d8 + 4);
;                 dot += (bflo(kw.x) * q0[0] + bfhi(kw.x) * q0[1]) + (bflo(kw.y) * q0[2] + bfhi(kw.y) * q0[3]) + (bflo(kw.z) * q1[0] + bfhi(kw.z) * q1[1]) + (bflo(kw.w) * q1[2] + bfhi(kw.w) * q1[3]); } }
;         else { const float* kp = ck + (((size_t)b * 2048 + idx) * 16 + h) * 64;
; #pragma unroll
;             for (int d4 = 0; d4 < 16; ++d4) { const f32x4 kv = *(const f32x4*)(kp + 4 * d4); const f32x4 qv = *(const LAS f32x4*)(sl + 4 * d4); dot += (kv[0] * qv[0] + kv[1] * qv[1]) + (kv[2] * qv[2] + kv[3] * qv[3]); } }
;         if (valid) { sl[64 + pat * 192 + j] = dot; mx = fmaxf(mx, dot); } }
	v_mul_f32_e32 v0, v0, v44
	v_mul_f32_e32 v4, v4, v44
	v_mul_f32_e32 v8, v8, v44
	v_mul_f32_e32 v12, v12, v44
	v_mul_f32_e32 v16, v16, v44
	v_mul_f32_e32 v20, v20, v44
	v_mul_f32_e32 v24, v24, v44
	v_mul_f32_e32 v28, v28, v44
	v_mul_f32_e32 v32, v32, v44
	v_mul_f32_e32 v36, v36, v44
	v_mul_f32_e32 v52, v52, v44
	v_fmac_f32_e32 v0, v1, v45
	v_fmac_f32_e32 v4, v5, v45
	v_fmac_f32_e32 v8, v9, v45
	v_fmac_f32_e32 v12, v13, v45
	v_fmac_f32_e32 v16, v17, v45
	v_fmac_f32_e32 v20, v21, v45
	v_fmac_f32_e32 v24, v25, v45
	v_fmac_f32_e32 v28, v29, v45
	v_fmac_f32_e32 v32, v33, v45
	v_fmac_f32_e32 v36, v37, v45
	v_fmac_f32_e32 v52, v53, v45
	v_fmac_f32_e32 v0, v2, v46
	v_fmac_f32_e32 v4, v6, v46
	v_fmac_f32_e32 v8, v10, v46
	v_fmac_f32_e32 v12, v14, v46
	v_fmac_f32_e32 v16, v18, v46
	v_fmac_f32_e32 v20, v22, v46
	v_fmac_f32_e32 v24, v26, v46
	v_fmac_f32_e32 v28, v30, v46
	v_fmac_f32_e32 v32, v34, v46
	v_fmac_f32_e32 v36, v38, v46
	v_fmac_f32_e32 v52, v54, v46
	v_fmac_f32_e32 v0, v3, v47
	v_fmac_f32_e32 v4, v7, v47
	v_fmac_f32_e32 v8, v11, v47
	v_fmac_f32_e32 v12, v15, v47
	v_fmac_f32_e32 v16, v19, v47
	v_fmac_f32_e32 v20, v23, v47
	v_fmac_f32_e32 v24, v27, v47
	v_fmac_f32_e32 v28, v31, v47
	v_fmac_f32_e32 v32, v35, v47
	v_fmac_f32_e32 v36, v39, v47
	v_fmac_f32_e32 v52, v55, v47
	s_nop 1
	v_add_f32_dpp v0, v0, v0 quad_perm:[1,0,3,2] row_mask:0xf bank_mask:0xf
	v_add_f32_dpp v4, v4, v4 quad_perm:[1,0,3,2] row_mask:0xf bank_mask:0xf
	v_add_f32_dpp v8, v8, v8 quad_perm:[1,0,3,2] row_mask:0xf bank_mask:0xf
	v_add_f32_dpp v12, v12, v12 quad_perm:[1,0,3,2] row_mask:0xf bank_mask:0xf
	v_add_f32_dpp v16, v16, v16 quad_perm:[1,0,3,2] row_mask:0xf bank_mask:0xf
	v_add_f32_dpp v20, v20, v20 quad_perm:[1,0,3,2] row_mask:0xf bank_mask:0xf
	v_add_f32_dpp v24, v24, v24 quad_perm:[1,0,3,2] row_mask:0xf bank_mask:0xf
	v_add_f32_dpp v28, v28, v28 quad_perm:[1,0,3,2] row_mask:0xf bank_mask:0xf
	v_add_f32_dpp v32, v32, v32 quad_perm:[1,0,3,2] row_mask:0xf bank_mask:0xf
	v_add_f32_dpp v36, v36, v36 quad_perm:[1,0,3,2] row_mask:0xf bank_mask:0xf
	v_add_f32_dpp v52, v52, v52 quad_perm:[1,0,3,2] row_mask:0xf bank_mask:0xf
	s_nop 1
	v_add_f32_dpp v0, v0, v0 quad_perm:[2,3,0,1] row_mask:0xf bank_mask:0xf
	v_add_f32_dpp v4, v4, v4 quad_perm:[2,3,0,1] row_mask:0xf bank_mask:0xf
	v_add_f32_dpp v8, v8, v8 quad_perm:[2,3,0,1] row_mask:0xf bank_mask:0xf
	v_add_f32_dpp v12, v12, v12 quad_perm:[2,3,0,1] row_mask:0xf bank_mask:0xf
	v_add_f32_dpp v16, v16, v16 quad_perm:[2,3,0,1] row_mask:0xf bank_mask:0xf
	v_add_f32_dpp v20, v20, v20 quad_perm:[2,3,0,1] row_mask:0xf bank_mask:0xf
	v_add_f32_dpp v24, v24, v24 quad_perm:[2,3,0,1] row_mask:0xf bank_mask:0xf
	v_add_f32_dpp v28, v28, v28 quad_perm:[2,3,0,1] row_mask:0xf bank_mask:0xf
	v_add_f32_dpp v32, v32, v32 quad_perm:[2,3,0,1] row_mask:0xf bank_mask:0xf
	v_add_f32_dpp v36, v36, v36 quad_perm:[2,3,0,1] row_mask:0xf bank_mask:0xf
	v_add_f32_dpp v52, v52, v52 quad_perm:[2,3,0,1] row_mask:0xf bank_mask:0xf
	s_nop 1
	v_add_f32_dpp v0, v0, v0 row_half_mirror row_mask:0xf bank_mask:0xf
	v_add_f32_dpp v4, v4, v4 row_half_mirror row_mask:0xf bank_mask:0xf
	v_add_f32_dpp v8, v8, v8 row_half_mirror row_mask:0xf bank_mask:0xf
	v_add_f32_dpp v12, v12, v12 row_half_mirror row_mask:0xf bank_mask:0xf
	v_add_f32_dpp v16, v16, v16 row_half_mirror row_mask:0xf bank_mask:0xf
	v_add_f32_dpp v20, v20, v20 row_half_mirror row_mask:0xf bank_mask:0xf
	v_add_f32_dpp v24, v24, v24 row_half_mirror row_mask:0xf bank_mask:0xf
	v_add_f32_dpp v28, v28, v28 row_half_mirror row_mask:0xf bank_mask:0xf
	v_add_f32_dpp v32, v32, v32 row_half_mirror row_mask:0xf bank_mask:0xf
	v_add_f32_dpp v36, v36, v36 row_half_mirror row_mask:0xf bank_mask:0xf
	v_add_f32_dpp v52, v52, v52 row_half_mirror row_mask:0xf bank_mask:0xf
	s_nop 1
	v_add_f32_dpp v0, v0, v0 row_mirror row_mask:0xf bank_mask:0xf
	v_add_f32_dpp v4, v4, v4 row_mirror row_mask:0xf bank_mask:0xf
	v_add_f32_dpp v8, v8, v8 row_mirror row_mask:0xf bank_mask:0xf
	v_add_f32_dpp v12, v12, v12 row_mirror row_mask:0xf bank_mask:0xf
	v_add_f32_dpp v16, v16, v16 row_mirror row_mask:0xf bank_mask:0xf
	v_add_f32_dpp v20, v20, v20 row_mirror row_mask:0xf bank_mask:0xf
	v_add_f32_dpp v24, v24, v24 row_mirror row_mask:0xf bank_mask:0xf
	v_add_f32_dpp v28, v28, v28 row_mirror row_mask:0xf bank_mask:0xf
	v_add_f32_dpp v32, v32, v32 row_mirror row_mask:0xf bank_mask:0xf
	v_add_f32_dpp v36, v36, v36 row_mirror row_mask:0xf bank_mask:0xf
	v_add_f32_dpp v52, v52, v52 row_mirror row_mask:0xf bank_mask:0xf
	s_nop 1
	s_mov_b32 s82, 0x10001
	s_mov_b32 s83, 0x10001
	s_mov_b64 exec, s[82:83]
	ds_write_b32 v48, v0 offset:944
	v_max_f32_e32 v40, v40, v0
	ds_write_b32 v48, v4 offset:960
	v_max_f32_e32 v40, v40, v4
	ds_write_b32 v48, v8 offset:976
	v_max_f32_e32 v40, v40, v8
	ds_write_b32 v48, v12 offset:992
	v_max_f32_e32 v40, v40, v12
	ds_write_b32 v48, v16 offset:1008
	v_max_f32_e32 v40, v40, v16
	ds_write_b32 v48, v20 offset:1024
	v_max_f32_e32 v40, v40, v20
	ds_write_b32 v48, v24 offset:1040
	v_max_f32_e32 v40, v40, v24
	ds_write_b32 v48, v28 offset:1056
	v_max_f32_e32 v40, v40, v28
	ds_write_b32 v48, v32 offset:1072
	v_max_f32_e32 v40, v40, v32
	ds_write_b32 v48, v36 offset:1088
	v_max_f32_e32 v40, v40, v36
	ds_write_b32 v48, v52 offset:1104
	v_max_f32_e32 v40, v40, v52
	s_mov_b64 exec, -1
	s_nop 4
	v_lshlrev_b32_e32 v49, 4, v41
	v_sub_u32_e32 v49, s2, v49
	v_min_i32_e32 v50, 0x7ff, v49
	v_lshl_add_u32 v49, v49, 12, v43
	v_lshl_add_u32 v50, v50, 12, v43
	s_mov_b64 s[76:77], s[84:85]
	global_load_dwordx4 v[0:3], v50, s[76:77] nt
	s_sub_u32 s76, s76, 0x40000
	s_subb_u32 s77, s77, 0
	global_load_dwordx4 v[4:7], v49, s[76:77] nt
	s_sub_u32 s76, s76, 0x40000
	s_subb_u32 s77, s77, 0
	global_load_dwordx4 v[8:11], v49, s[76:77] nt
	s_sub_u32 s76, s76, 0x40000
	s_subb_u32 s77, s77, 0
	global_load_dwordx4 v[12:15], v49, s[76:77] nt
	s_sub_u32 s76, s76, 0x40000
	s_subb_u32 s77, s77, 0
	global_load_dwordx4 v[16:19], v49, s[76:77] nt
	s_sub_u32 s76, s76, 0x40000
	s_subb_u32 s77, s77, 0
	global_load_dwordx4 v[20:23], v49, s[76:77] nt
	s_sub_u32 s76, s76, 0x40000
	s_subb_u32 s77, s77, 0
	global_load_dwordx4 v[24:27], v49, s[76:77] nt
	s_sub_u32 s76, s76, 0x40000
	s_subb_u32 s77, s77, 0
	global_load_dwordx4 v[28:31], v49, s[76:77] nt
	s_sub_u32 s76, s76, 0x40000
	s_subb_u32 s77, s77, 0
	global_load_dwordx4 v[32:35], v49, s[76:77] nt
	s_sub_u32 s76, s76, 0x40000
	s_subb_u32 s77, s77, 0
	global_load_dwordx4 v[36:39], v49, s[76:77] nt
	s_sub_u32 s76, s76, 0x40000
	s_subb_u32 s77, s77, 0
	global_load_dwordx4 v[52:55], v49, s[76:77] nt
	s_sub_u32 s76, s76, 0x40000
	s_subb_u32 s77, s77, 0
	s_waitcnt vmcnt(11)
; #define LAS __attribute__((address_space(3)))
; DI float bflo(unsigned w) { return __uint_as_float(w << 16); }
; DI float bfhi(unsigned w) { return __uint_as_float(w & 0xffff0000u); }
; DI void attn_sample_unit(const Params& p, int u, const bf16_t* Q, const bf16_t* Kb, const bf16_t* Vb, bf16_t* att, LAS float* sl, int lane) {
;     ...
;     for (int e = 0; e < 9; ++e) { const int pat = e / 3, r = e - 3 * pat; const int dil = 1 << (2 * pat);
;         const int j = lane + 64 * r; const bool valid = j <= 128; const int idx = 2048 + t - dil * (valid ? j : 0);
;         float dot = 0.f;
;         if (idx >= 2048) { const bf16_t* kp = Kb + ((size_t)NP + b * 4 + (idx - 2048)) * 1024 + h * 64;
; #pragma unroll
;             for (int d8 = 0; d8 < 8; ++d8) { const u32x4 kw = *(const u32x4*)(kp + 8 * d8); const f32x4 q0 = *(const LAS f32x4*)(sl + 8 * d8), q1 = *(const LAS f32x4*)(sl + 8 * d8 + 4);
;                 dot += (bflo(kw.x) * q0[0] + bfhi(kw.x) * q0[1]) + (bflo(kw.y) * q0[2] + bfhi(kw.y) * q0[3]) + (bflo(kw.z) * q1[0] + bfhi(kw.z) * q1[1]) + (bflo(kw.w) * q1[2] + bfhi(kw.w) * q1[3]); } }
;         else { const float* kp = ck + (((size_t)b * 2048 + idx) * 16 + h) * 64;
; #pragma unroll
;             for (int d4 = 0; d4 < 16; ++d4) { const f32x4 kv = *(const f32x4*)(kp + 4 * d4); const f32x4 qv = *(const LAS f32x4*)(sl + 4 * d4); dot += (kv[0] * qv[0] + kv[1] * qv[1]) + (kv[2] * qv[2] + kv[3] * qv[3]); } }
;         if (valid) { sl[64 + pat * 192 + j] = dot; mx = fmaxf(mx, dot); } }
	v_mul_f32_e32 v56, v56, v44
	v_mul_f32_e32 v60, v60, v44
	v_mul_f32_e32 v64, v64, v44
	v_mul_f32_e32 v68, v68, v44
	v_mul_f32_e32 v72, v72, v44
	v_mul_f32_e32 v76, v76, v44
	v_mul_f32_e32 v80, v80, v44
	v_mul_f32_e32 v84, v84, v44
	v_mul_f32_e32 v88, v88, v44
	v_mul_f32_e32 v92, v92, v44
	v_mul_f32_e32 v96, v96, v44
	v_fmac_f32_e32 v56, v57, v45
	v_fmac_f32_e32 v60, v61, v45
	v_fmac_f32_e32 v64, v65, v45
	v_fmac_f32_e32 v68, v69, v45
	v_fmac_f32_e32 v72, v73, v45
	v_fmac_f32_e32 v76, v77, v45
	v_fmac_f32_e32 v80, v81, v45
	v_fmac_f32_e32 v84, v85, v45
	v_fmac_f32_e32 v88, v89, v45
	v_fmac_f32_e32 v92, v93, v45
	v_fmac_f32_e32 v96, v97, v45
	v_fmac_f32_e32 v56, v58, v46
	v_fmac_f32_e32 v60, v62, v46
	v_fmac_f32_e32 v64, v66, v46
	v_fmac_f32_e32 v68, v70, v46
	v_fmac_f32_e32 v72, v74, v46
	v_fmac_f32_e32 v76, v78, v46
	v_fmac_f32_e32 v80, v82, v46
	v_fmac_f32_e32 v84, v86, v46
	v_fmac_f32_e32 v88, v90, v46
	v_fmac_f32_e32 v92, v94, v46
	v_fmac_f32_e32 v96, v98, v46
	v_fmac_f32_e32 v56, v59, v47
	v_fmac_f32_e32 v60, v63, v47
	v_fmac_f32_e32 v64, v67, v47
	v_fmac_f32_e32 v68, v71, v47
	v_fmac_f32_e32 v72, v75, v47
	v_fmac_f32_e32 v76, v79, v47
	v_fmac_f32_e32 v80, v83, v47
	v_fmac_f32_e32 v84, v87, v47
	v_fmac_f32_e32 v88, v91, v47
	v_fmac_f32_e32 v92, v95, v47
	v_fmac_f32_e32 v96, v99, v47
	s_nop 1
	v_add_f32_dpp v56, v56, v56 quad_perm:[1,0,3,2] row_mask:0xf bank_mask:0xf
	v_add_f32_dpp v60, v60, v60 quad_perm:[1,0,3,2] row_mask:0xf bank_mask:0xf
	v_add_f32_dpp v64, v64, v64 quad_perm:[1,0,3,2] row_mask:0xf bank_mask:0xf
	v_add_f32_dpp v68, v68, v68 quad_perm:[1,0,3,2] row_mask:0xf bank_mask:0xf
	v_add_f32_dpp v72, v72, v72 quad_perm:[1,0,3,2] row_mask:0xf bank_mask:0xf
	v_add_f32_dpp v76, v76, v76 quad_perm:[1,0,3,2] row_mask:0xf bank_mask:0xf
	v_add_f32_dpp v80, v80, v80 quad_perm:[1,0,3,2] row_mask:0xf bank_mask:0xf
	v_add_f32_dpp v84, v84, v84 quad_perm:[1,0,3,2] row_mask:0xf bank_mask:0xf
	v_add_f32_dpp v88, v88, v88 quad_perm:[1,0,3,2] row_mask:0xf bank_mask:0xf
	v_add_f32_dpp v92, v92, v92 quad_perm:[1,0,3,2] row_mask:0xf bank_mask:0xf
	v_add_f32_dpp v96, v96, v96 quad_perm:[1,0,3,2] row_mask:0xf bank_mask:0xf
	s_nop 1
	v_add_f32_dpp v56, v56, v56 quad_perm:[2,3,0,1] row_mask:0xf bank_mask:0xf
	v_add_f32_dpp v60, v60, v60 quad_perm:[2,3,0,1] row_mask:0xf bank_mask:0xf
	v_add_f32_dpp v64, v64, v64 quad_perm:[2,3,0,1] row_mask:0xf bank_mask:0xf
	v_add_f32_dpp v68, v68, v68 quad_perm:[2,3,0,1] row_mask:0xf bank_mask:0xf
	v_add_f32_dpp v72, v72, v72 quad_perm:[2,3,0,1] row_mask:0xf bank_mask:0xf
	v_add_f32_dpp v76, v76, v76 quad_perm:[2,3,0,1] row_mask:0xf bank_mask:0xf
	v_add_f32_dpp v80, v80, v80 quad_perm:[2,3,0,1] row_mask:0xf bank_mask:0xf
	v_add_f32_dpp v84, v84, v84 quad_perm:[2,3,0,1] row_mask:0xf bank_mask:0xf
	v_add_f32_dpp v88, v88, v88 quad_perm:[2,3,0,1] row_mask:0xf bank_mask:0xf
	v_add_f32_dpp v92, v92, v92 quad_perm:[2,3,0,1] row_mask:0xf bank_mask:0xf
	v_add_f32_dpp v96, v96, v96 quad_perm:[2,3,0,1] row_mask:0xf bank_mask:0xf
	s_nop 1
	v_add_f32_dpp v56, v56, v56 row_half_mirror row_mask:0xf bank_mask:0xf
	v_add_f32_dpp v60, v60, v60 row_half_mirror row_mask:0xf bank_mask:0xf
	v_add_f32_dpp v64, v64, v64 row_half_mirror row_mask:0xf bank_mask:0xf
	v_add_f32_dpp v68, v68, v68 row_half_mirror row_mask:0xf bank_mask:0xf
	v_add_f32_dpp v72, v72, v72 row_half_mirror row_mask:0xf bank_mask:0xf
	v_add_f32_dpp v76, v76, v76 row_half_mirror row_mask:0xf bank_mask:0xf
	v_add_f32_dpp v80, v80, v80 row_half_mirror row_mask:0xf bank_mask:0xf
	v_add_f32_dpp v84, v84, v84 row_half_mirror row_mask:0xf bank_mask:0xf
	v_add_f32_dpp v88, v88, v88 row_half_mirror row_mask:0xf bank_mask:0xf
	v_add_f32_dpp v92, v92, v92 row_half_mirror row_mask:0xf bank_mask:0xf
	v_add_f32_dpp v96, v96, v96 row_half_mirror row_mask:0xf bank_mask:0xf
	s_nop 1
	v_add_f32_dpp v56, v56, v56 row_mirror row_mask:0xf bank_mask:0xf
	v_add_f32_dpp v60, v60, v60 row_mirror row_mask:0xf bank_mask:0xf
	v_add_f32_dpp v64, v64, v64 row_mirror row_mask:0xf bank_mask:0xf
	v_add_f32_dpp v68, v68, v68 row_mirror row_mask:0xf bank_mask:0xf
	v_add_f32_dpp v72, v72, v72 row_mirror row_mask:0xf bank_mask:0xf
	v_add_f32_dpp v76, v76, v76 row_mirror row_mask:0xf bank_mask:0xf
	v_add_f32_dpp v80, v80, v80 row_mirror row_mask:0xf bank_mask:0xf
	v_add_f32_dpp v84, v84, v84 row_mirror row_mask:0xf bank_mask:0xf
	v_add_f32_dpp v88, v88, v88 row_mirror row_mask:0xf bank_mask:0xf
	v_add_f32_dpp v92, v92, v92 row_mirror row_mask:0xf bank_mask:0xf
	v_add_f32_dpp v96, v96, v96 row_mirror row_mask:0xf bank_mask:0xf
	s_nop 1
	s_mov_b32 s82, 0x10001
	s_mov_b32 s83, 0x10001
	s_mov_b64 exec, s[82:83]
	ds_write_b32 v48, v56 offset:1120
	v_max_f32_e32 v40, v40, v56
	ds_write_b32 v48, v60 offset:1136
	v_max_f32_e32 v40, v40, v60
	ds_write_b32 v48, v64 offset:1152
	v_max_f32_e32 v40, v40, v64
	ds_write_b32 v48, v68 offset:1168
	v_max_f32_e32 v40, v40, v68
	ds_write_b32 v48, v72 offset:1184
	v_max_f32_e32 v40, v40, v72
	ds_write_b32 v48, v76 offset:1200
	v_max_f32_e32 v40, v40, v76
	ds_write_b32 v48, v80 offset:1216
	v_max_f32_e32 v40, v40, v80
	ds_write_b32 v48, v84 offset:1232
	v_max_f32_e32 v40, v40, v84
	ds_write_b32 v48, v88 offset:1248
	v_max_f32_e32 v40, v40, v88
	ds_write_b32 v48, v92 offset:1264
	v_max_f32_e32 v40, v40, v92
	s_mov_b64 exec, 1
	ds_write_b32 v48, v96 offset:1280
	v_max_f32_e32 v40, v40, v96
	s_mov_b64 exec, -1
	s_nop 4
	global_load_dwordx4 v[56:59], v49, s[76:77] nt
	s_sub_u32 s76, s76, 0x40000
	s_subb_u32 s77, s77, 0
	global_load_dwordx4 v[60:63], v49, s[76:77] nt
	s_sub_u32 s76, s76, 0x40000
	s_subb_u32 s77, s77, 0
	global_load_dwordx4 v[64:67], v49, s[76:77] nt
	s_sub_u32 s76, s76, 0x40000
	s_subb_u32 s77, s77, 0
	global_load_dwordx4 v[68:71], v49, s[76:77] nt
	s_sub_u32 s76, s76, 0x40000
	s_subb_u32 s77, s77, 0
	global_load_dwordx4 v[72:75], v49, s[76:77] nt
	s_sub_u32 s76, s76, 0x40000
	s_subb_u32 s77, s77, 0
	global_load_dwordx4 v[76:79], v49, s[76:77] nt
	s_sub_u32 s76, s76, 0x40000
	s_subb_u32 s77, s77, 0
	global_load_dwordx4 v[80:83], v49, s[76:77] nt
	s_sub_u32 s76, s76, 0x40000
	s_subb_u32 s77, s77, 0
	global_load_dwordx4 v[84:87], v49, s[76:77] nt
	s_sub_u32 s76, s76, 0x40000
	s_subb_u32 s77, s77, 0
	global_load_dwordx4 v[88:91], v49, s[76:77] nt
	s_sub_u32 s76, s76, 0x40000
	s_subb_u32 s77, s77, 0
	global_load_dwordx4 v[92:95], v49, s[76:77] nt
	s_sub_u32 s76, s76, 0x40000
	s_subb_u32 s77, s77, 0
	global_load_dwordx4 v[96:99], v49, s[76:77] nt
	s_sub_u32 s76, s76, 0x40000
	s_subb_u32 s77, s77, 0
	s_waitcnt vmcnt(11)
; #define LAS __attribute__((address_space(3)))
; DI float bflo(unsigned w) { return __uint_as_float(w << 16); }
; DI float bfhi(unsigned w) { return __uint_as_float(w & 0xffff0000u); }
; DI void attn_sample_unit(const Params& p, int u, const bf16_t* Q, const bf16_t* Kb, const bf16_t* Vb, bf16_t* att, LAS float* sl, int lane) {
;     ...
;     for (int e = 0; e < 9; ++e) { const int pat = e / 3, r = e - 3 * pat; const int dil = 1 << (2 * pat);
;         const int j = lane + 64 * r; const bool valid = j <= 128; const int idx = 2048 + t - dil * (valid ? j : 0);
;         float dot = 0.f;
;         if (idx >= 2048) { const bf16_t* kp = Kb + ((size_t)NP + b * 4 + (idx - 2048)) * 1024 + h * 64;
; #pragma unroll
;             for (int d8 = 0; d8 < 8; ++d8) { const u32x4 kw = *(const u32x4*)(kp + 8 * d8); const f32x4 q0 = *(const LAS f32x4*)(sl + 8 * d8), q1 = *(const LAS f32x4*)(sl + 8 * d8 + 4);
;                 dot += (bflo(kw.x) * q0[0] + bfhi(kw.x) * q0[1]) + (bflo(kw.y) * q0[2] + bfhi(kw.y) * q0[3]) + (bflo(kw.z) * q1[0] + bfhi(kw.z) * q1[1]) + (bflo(kw.w) * q1[2] + bfhi(kw.w) * q1[3]); } }
;         else { const float* kp = ck + (((size_t)b * 2048 + idx) * 16 + h) * 64;
; #pragma unroll
;             for (int d4 = 0; d4 < 16; ++d4) { const f32x4 kv = *(const f32x4*)(kp + 4 * d4); const f32x4 qv = *(const LAS f32x4*)(sl + 4 * d4); dot += (kv[0] * qv[0] + kv[1] * qv[1]) + (kv[2] * qv[2] + kv[3] * qv[3]); } }
;         if (valid) { sl[64 + pat * 192 + j] = dot; mx = fmaxf(mx, dot); } }
	v_mul_f32_e32 v0, v0, v44
	v_mul_f32_e32 v4, v4, v44
	v_mul_f32_e32 v8, v8, v44
	v_mul_f32_e32 v12, v12, v44
	v_mul_f32_e32 v16, v16, v44
	v_mul_f32_e32 v20, v20, v44
	v_mul_f32_e32 v24, v24, v44
	v_mul_f32_e32 v28, v28, v44
	v_mul_f32_e32 v32, v32, v44
	v_mul_f32_e32 v36, v36, v44
	v_mul_f32_e32 v52, v52, v44
	v_fmac_f32_e32 v0, v1, v45
	v_fmac_f32_e32 v4, v5, v45
	v_fmac_f32_e32 v8, v9, v45
	v_fmac_f32_e32 v12, v13, v45
	v_fmac_f32_e32 v16, v17, v45
	v_fmac_f32_e32 v20, v21, v45
	v_fmac_f32_e32 v24, v25, v45
	v_fmac_f32_e32 v28, v29, v45
	v_fmac_f32_e32 v32, v33, v45
	v_fmac_f32_e32 v36, v37, v45
	v_fmac_f32_e32 v52, v53, v45
	v_fmac_f32_e32 v0, v2, v46
	v_fmac_f32_e32 v4, v6, v46
	v_fmac_f32_e32 v8, v10, v46
	v_fmac_f32_e32 v12, v14, v46
	v_fmac_f32_e32 v16, v18, v46
	v_fmac_f32_e32 v20, v22, v46
	v_fmac_f32_e32 v24, v26, v46
	v_fmac_f32_e32 v28, v30, v46
	v_fmac_f32_e32 v32, v34, v46
	v_fmac_f32_e32 v36, v38, v46
	v_fmac_f32_e32 v52, v54, v46
	v_fmac_f32_e32 v0, v3, v47
	v_fmac_f32_e32 v4, v7, v47
	v_fmac_f32_e32 v8, v11, v47
	v_fmac_f32_e32 v12, v15, v47
	v_fmac_f32_e32 v16, v19, v47
	v_fmac_f32_e32 v20, v23, v47
	v_fmac_f32_e32 v24, v27, v47
	v_fmac_f32_e32 v28, v31, v47
	v_fmac_f32_e32 v32, v35, v47
	v_fmac_f32_e32 v36, v39, v47
	v_fmac_f32_e32 v52, v55, v47
	s_nop 1
	v_add_f32_dpp v0, v0, v0 quad_perm:[1,0,3,2] row_mask:0xf bank_mask:0xf
	v_add_f32_dpp v4, v4, v4 quad_perm:[1,0,3,2] row_mask:0xf bank_mask:0xf
	v_add_f32_dpp v8, v8, v8 quad_perm:[1,0,3,2] row_mask:0xf bank_mask:0xf
	v_add_f32_dpp v12, v12, v12 quad_perm:[1,0,3,2] row_mask:0xf bank_mask:0xf
	v_add_f32_dpp v16, v16, v16 quad_perm:[1,0,3,2] row_mask:0xf bank_mask:0xf
	v_add_f32_dpp v20, v20, v20 quad_perm:[1,0,3,2] row_mask:0xf bank_mask:0xf
	v_add_f32_dpp v24, v24, v24 quad_perm:[1,0,3,2] row_mask:0xf bank_mask:0xf
	v_add_f32_dpp v28, v28, v28 quad_perm:[1,0,3,2] row_mask:0xf bank_mask:0xf
	v_add_f32_dpp v32, v32, v32 quad_perm:[1,0,3,2] row_mask:0xf bank_mask:0xf
	v_add_f32_dpp v36, v36, v36 quad_perm:[1,0,3,2] row_mask:0xf bank_mask:0xf
	v_add_f32_dpp v52, v52, v52 quad_perm:[1,0,3,2] row_mask:0xf bank_mask:0xf
	s_nop 1
	v_add_f32_dpp v0, v0, v0 quad_perm:[2,3,0,1] row_mask:0xf bank_mask:0xf
	v_add_f32_dpp v4, v4, v4 quad_perm:[2,3,0,1] row_mask:0xf bank_mask:0xf
	v_add_f32_dpp v8, v8, v8 quad_perm:[2,3,0,1] row_mask:0xf bank_mask:0xf
	v_add_f32_dpp v12, v12, v12 quad_perm:[2,3,0,1] row_mask:0xf bank_mask:0xf
	v_add_f32_dpp v16, v16, v16 quad_perm:[2,3,0,1] row_mask:0xf bank_mask:0xf
	v_add_f32_dpp v20, v20, v20 quad_perm:[2,3,0,1] row_mask:0xf bank_mask:0xf
	v_add_f32_dpp v24, v24, v24 quad_perm:[2,3,0,1] row_mask:0xf bank_mask:0xf
	v_add_f32_dpp v28, v28, v28 quad_perm:[2,3,0,1] row_mask:0xf bank_mask:0xf
	v_add_f32_dpp v32, v32, v32 quad_perm:[2,3,0,1] row_mask:0xf bank_mask:0xf
	v_add_f32_dpp v36, v36, v36 quad_perm:[2,3,0,1] row_mask:0xf bank_mask:0xf
	v_add_f32_dpp v52, v52, v52 quad_perm:[2,3,0,1] row_mask:0xf bank_mask:0xf
	s_nop 1
	v_add_f32_dpp v0, v0, v0 row_half_mirror row_mask:0xf bank_mask:0xf
	v_add_f32_dpp v4, v4, v4 row_half_mirror row_mask:0xf bank_mask:0xf
	v_add_f32_dpp v8, v8, v8 row_half_mirror row_mask:0xf bank_mask:0xf
	v_add_f32_dpp v12, v12, v12 row_half_mirror row_mask:0xf bank_mask:0xf
	v_add_f32_dpp v16, v16, v16 row_half_mirror row_mask:0xf bank_mask:0xf
	v_add_f32_dpp v20, v20, v20 row_half_mirror row_mask:0xf bank_mask:0xf
	v_add_f32_dpp v24, v24, v24 row_half_mirror row_mask:0xf bank_mask:0xf
	v_add_f32_dpp v28, v28, v28 row_half_mirror row_mask:0xf bank_mask:0xf
	v_add_f32_dpp v32, v32, v32 row_half_mirror row_mask:0xf bank_mask:0xf
	v_add_f32_dpp v36, v36, v36 row_half_mirror row_mask:0xf bank_mask:0xf
	v_add_f32_dpp v52, v52, v52 row_half_mirror row_mask:0xf bank_mask:0xf
	s_nop 1
	v_add_f32_dpp v0, v0, v0 row_mirror row_mask:0xf bank_mask:0xf
	v_add_f32_dpp v4, v4, v4 row_mirror row_mask:0xf bank_mask:0xf
	v_add_f32_dpp v8, v8, v8 row_mirror row_mask:0xf bank_mask:0xf
	v_add_f32_dpp v12, v12, v12 row_mirror row_mask:0xf bank_mask:0xf
	v_add_f32_dpp v16, v16, v16 row_mirror row_mask:0xf bank_mask:0xf
	v_add_f32_dpp v20, v20, v20 row_mirror row_mask:0xf bank_mask:0xf
	v_add_f32_dpp v24, v24, v24 row_mirror row_mask:0xf bank_mask:0xf
	v_add_f32_dpp v28, v28, v28 row_mirror row_mask:0xf bank_mask:0xf
	v_add_f32_dpp v32, v32, v32 row_mirror row_mask:0xf bank_mask:0xf
	v_add_f32_dpp v36, v36, v36 row_mirror row_mask:0xf bank_mask:0xf
	v_add_f32_dpp v52, v52, v52 row_mirror row_mask:0xf bank_mask:0xf
	s_nop 1
	s_mov_b32 s82, 0x10000
	s_mov_b32 s83, 0x10001
	s_mov_b64 exec, s[82:83]
	ds_write_b32 v48, v0 offset:1536
	v_max_f32_e32 v40, v40, v0
	s_mov_b32 s82, 0x10001
	s_mov_b32 s83, 0x10001
	s_mov_b64 exec, s[82:83]
	ds_write_b32 v48, v4 offset:1552
	v_max_f32_e32 v40, v40, v4
	ds_write_b32 v48, v8 offset:1568
	v_max_f32_e32 v40, v40, v8
	ds_write_b32 v48, v12 offset:1584
	v_max_f32_e32 v40, v40, v12
	ds_write_b32 v48, v16 offset:1600
	v_max_f32_e32 v40, v40, v16
	ds_write_b32 v48, v20 offset:1616
	v_max_f32_e32 v40, v40, v20
	ds_write_b32 v48, v24 offset:1632
	v_max_f32_e32 v40, v40, v24
	ds_write_b32 v48, v28 offset:1648
	v_max_f32_e32 v40, v40, v28
	ds_write_b32 v48, v32 offset:1664
	v_max_f32_e32 v40, v40, v32
	ds_write_b32 v48, v36 offset:1680
	v_max_f32_e32 v40, v40, v36
	ds_write_b32 v48, v52 offset:1696
	v_max_f32_e32 v40, v40, v52
	s_mov_b64 exec, -1
	s_nop 4
	global_load_dwordx4 v[0:3], v49, s[76:77] nt
	s_sub_u32 s76, s76, 0x40000
	s_subb_u32 s77, s77, 0
	global_load_dwordx4 v[4:7], v49, s[76:77] nt
	s_sub_u32 s76, s76, 0x40000
	s_subb_u32 s77, s77, 0
	global_load_dwordx4 v[8:11], v49, s[76:77] nt
	s_sub_u32 s76, s76, 0x40000
	s_subb_u32 s77, s77, 0
	global_load_dwordx4 v[12:15], v49, s[76:77] nt
	s_sub_u32 s76, s76, 0x40000
	s_subb_u32 s77, s77, 0
	global_load_dwordx4 v[16:19], v49, s[76:77] nt
	s_sub_u32 s76, s76, 0x40000
	s_subb_u32 s77, s77, 0
	global_load_dwordx4 v[20:23], v49, s[76:77] nt
	s_sub_u32 s76, s76, 0x40000
	s_subb_u32 s77, s77, 0
	global_load_dwordx4 v[24:27], v49, s[76:77] nt
	s_sub_u32 s76, s76, 0x40000
	s_subb_u32 s77, s77, 0
	global_load_dwordx4 v[28:31], v49, s[76:77] nt
	s_sub_u32 s76, s76, 0x40000
	s_subb_u32 s77, s77, 0
	global_load_dwordx4 v[32:35], v49, s[76:77] nt
	s_sub_u32 s76, s76, 0x40000
	s_subb_u32 s77, s77, 0
	global_load_dwordx4 v[36:39], v49, s[76:77] nt
	s_sub_u32 s76, s76, 0x40000
	s_subb_u32 s77, s77, 0
	s_mov_b64 exec, 0xffff
	global_load_dwordx4 v[52:55], v49, s[76:77] nt
	s_mov_b64 exec, -1
	s_waitcnt vmcnt(11)
; #define LAS __attribute__((address_space(3)))
; DI void attn_sample_unit(const Params& p, int u, const bf16_t* Q, const bf16_t* Kb, const bf16_t* Vb, bf16_t* att, LAS float* sl, int lane) {
;     ...
;         else { const float* kp = ck + (((size_t)b * 2048 + idx) * 16 + h) * 64;
; #pragma unroll
;             for (int d4 = 0; d4 < 16; ++d4) { const f32x4 kv = *(const f32x4*)(kp + 4 * d4); const f32x4 qv = *(const LAS f32x4*)(sl + 4 * d4); dot += (kv[0] * qv[0] + kv[1] * qv[1]) + (kv[2] * qv[2] + kv[3] * qv[3]); } }
;         if (valid) { sl[64 + pat * 192 + j] = dot; mx = fmaxf(mx, dot); } }
	v_mul_f32_e32 v56, v56, v44
	v_mul_f32_e32 v60, v60, v44
	v_mul_f32_e32 v64, v64, v44
	v_mul_f32_e32 v68, v68, v44
	v_mul_f32_e32 v72, v72, v44
	v_mul_f32_e32 v76, v76, v44
	v_mul_f32_e32 v80, v80, v44
	v_mul_f32_e32 v84, v84, v44
	v_mul_f32_e32 v88, v88, v44
	v_mul_f32_e32 v92, v92, v44
	v_mul_f32_e32 v96, v96, v44
	v_fmac_f32_e32 v56, v57, v45
	v_fmac_f32_e32 v60, v61, v45
	v_fmac_f32_e32 v64, v65, v45
	v_fmac_f32_e32 v68, v69, v45
	v_fmac_f32_e32 v72, v73, v45
	v_fmac_f32_e32 v76, v77, v45
	v_fmac_f32_e32 v80, v81, v45
	v_fmac_f32_e32 v84, v85, v45
	v_fmac_f32_e32 v88, v89, v45
	v_fmac_f32_e32 v92, v93, v45
	v_fmac_f32_e32 v96, v97, v45
	v_fmac_f32_e32 v56, v58, v46
	v_fmac_f32_e32 v60, v62, v46
	v_fmac_f32_e32 v64, v66, v46
	v_fmac_f32_e32 v68, v70, v46
	v_fmac_f32_e32 v72, v74, v46
	v_fmac_f32_e32 v76, v78, v46
	v_fmac_f32_e32 v80, v82, v46
	v_fmac_f32_e32 v84, v86, v46
	v_fmac_f32_e32 v88, v90, v46
	v_fmac_f32_e32 v92, v94, v46
	v_fmac_f32_e32 v96, v98, v46
	v_fmac_f32_e32 v56, v59, v47
	v_fmac_f32_e32 v60, v63, v47
	v_fmac_f32_e32 v64, v67, v47
	v_fmac_f32_e32 v68, v71, v47
	v_fmac_f32_e32 v72, v75, v47
	v_fmac_f32_e32 v76, v79, v47
	v_fmac_f32_e32 v80, v83, v47
	v_fmac_f32_e32 v84, v87, v47
	v_fmac_f32_e32 v88, v91, v47
	v_fmac_f32_e32 v92, v95, v47
	v_fmac_f32_e32 v96, v99, v47
	s_nop 1
	v_add_f32_dpp v56, v56, v56 quad_perm:[1,0,3,2] row_mask:0xf bank_mask:0xf
	v_add_f32_dpp v60, v60, v60 quad_perm:[1,0,3,2] row_mask:0xf bank_mask:0xf
	v_add_f32_dpp v64, v64, v64 quad_perm:[1,0,3,2] row_mask:0xf bank_mask:0xf
	v_add_f32_dpp v68, v68, v68 quad_perm:[1,0,3,2] row_mask:0xf bank_mask:0xf
	v_add_f32_dpp v72, v72, v72 quad_perm:[1,0,3,2] row_mask:0xf bank_mask:0xf
	v_add_f32_dpp v76, v76, v76 quad_perm:[1,0,3,2] row_mask:0xf bank_mask:0xf
	v_add_f32_dpp v80, v80, v80 quad_perm:[1,0,3,2] row_mask:0xf bank_mask:0xf
	v_add_f32_dpp v84, v84, v84 quad_perm:[1,0,3,2] row_mask:0xf bank_mask:0xf
	v_add_f32_dpp v88, v88, v88 quad_perm:[1,0,3,2] row_mask:0xf bank_mask:0xf
	v_add_f32_dpp v92, v92, v92 quad_perm:[1,0,3,2] row_mask:0xf bank_mask:0xf
	v_add_f32_dpp v96, v96, v96 quad_perm:[1,0,3,2] row_mask:0xf bank_mask:0xf
	s_nop 1
	v_add_f32_dpp v56, v56, v56 quad_perm:[2,3,0,1] row_mask:0xf bank_mask:0xf
	v_add_f32_dpp v60, v60, v60 quad_perm:[2,3,0,1] row_mask:0xf bank_mask:0xf
	v_add_f32_dpp v64, v64, v64 quad_perm:[2,3,0,1] row_mask:0xf bank_mask:0xf
	v_add_f32_dpp v68, v68, v68 quad_perm:[2,3,0,1] row_mask:0xf bank_mask:0xf
	v_add_f32_dpp v72, v72, v72 quad_perm:[2,3,0,1] row_mask:0xf bank_mask:0xf
	v_add_f32_dpp v76, v76, v76 quad_perm:[2,3,0,1] row_mask:0xf bank_mask:0xf
	v_add_f32_dpp v80, v80, v80 quad_perm:[2,3,0,1] row_mask:0xf bank_mask:0xf
	v_add_f32_dpp v84, v84, v84 quad_perm:[2,3,0,1] row_mask:0xf bank_mask:0xf
	v_add_f32_dpp v88, v88, v88 quad_perm:[2,3,0,1] row_mask:0xf bank_mask:0xf
	v_add_f32_dpp v92, v92, v92 quad_perm:[2,3,0,1] row_mask:0xf bank_mask:0xf
	v_add_f32_dpp v96, v96, v96 quad_perm:[2,3,0,1] row_mask:0xf bank_mask:0xf
	s_nop 1
	v_add_f32_dpp v56, v56, v56 row_half_mirror row_mask:0xf bank_mask:0xf
	v_add_f32_dpp v60, v60, v60 row_half_mirror row_mask:0xf bank_mask:0xf
	v_add_f32_dpp v64, v64, v64 row_half_mirror row_mask:0xf bank_mask:0xf
	v_add_f32_dpp v68, v68, v68 row_half_mirror row_mask:0xf bank_mask:0xf
	v_add_f32_dpp v72, v72, v72 row_half_mirror row_mask:0xf bank_mask:0xf
	v_add_f32_dpp v76, v76, v76 row_half_mirror row_mask:0xf bank_mask:0xf
	v_add_f32_dpp v80, v80, v80 row_half_mirror row_mask:0xf bank_mask:0xf
	v_add_f32_dpp v84, v84, v84 row_half_mirror row_mask:0xf bank_mask:0xf
	v_add_f32_dpp v88, v88, v88 row_half_mirror row_mask:0xf bank_mask:0xf
	v_add_f32_dpp v92, v92, v92 row_half_mirror row_mask:0xf bank_mask:0xf
	v_add_f32_dpp v96, v96, v96 row_half_mirror row_mask:0xf bank_mask:0xf
	s_nop 1
	v_add_f32_dpp v56, v56, v56 row_mirror row_mask:0xf bank_mask:0xf
	v_add_f32_dpp v60, v60, v60 row_mirror row_mask:0xf bank_mask:0xf
	v_add_f32_dpp v64, v64, v64 row_mirror row_mask:0xf bank_mask:0xf
	v_add_f32_dpp v68, v68, v68 row_mirror row_mask:0xf bank_mask:0xf
	v_add_f32_dpp v72, v72, v72 row_mirror row_mask:0xf bank_mask:0xf
	v_add_f32_dpp v76, v76, v76 row_mirror row_mask:0xf bank_mask:0xf
	v_add_f32_dpp v80, v80, v80 row_mirror row_mask:0xf bank_mask:0xf
	v_add_f32_dpp v84, v84, v84 row_mirror row_mask:0xf bank_mask:0xf
	v_add_f32_dpp v88, v88, v88 row_mirror row_mask:0xf bank_mask:0xf
	v_add_f32_dpp v92, v92, v92 row_mirror row_mask:0xf bank_mask:0xf
	v_add_f32_dpp v96, v96, v96 row_mirror row_mask:0xf bank_mask:0xf
	s_nop 1
	s_mov_b32 s82, 0x10001
	s_mov_b32 s83, 0x10001
	s_mov_b64 exec, s[82:83]
	ds_write_b32 v48, v56 offset:1712
	v_max_f32_e32 v40, v40, v56
	ds_write_b32 v48, v60 offset:1728
	v_max_f32_e32 v40, v40, v60
	ds_write_b32 v48, v64 offset:1744
	v_max_f32_e32 v40, v40, v64
	ds_write_b32 v48, v68 offset:1760
	v_max_f32_e32 v40, v40, v68
	ds_write_b32 v48, v72 offset:1776
	v_max_f32_e32 v40, v40, v72
	ds_write_b32 v48, v76 offset:1792
	v_max_f32_e32 v40, v40, v76
	ds_write_b32 v48, v80 offset:1808
	v_max_f32_e32 v40, v40, v80
	ds_write_b32 v48, v84 offset:1824
	v_max_f32_e32 v40, v40, v84
	ds_write_b32 v48, v88 offset:1840
	v_max_f32_e32 v40, v40, v88
	ds_write_b32 v48, v92 offset:1856
	v_max_f32_e32 v40, v40, v92
	ds_write_b32 v48, v96 offset:1872
	v_max_f32_e32 v40, v40, v96
	s_mov_b64 exec, -1
	s_nop 4
	s_waitcnt vmcnt(0)
; #define LAS __attribute__((address_space(3)))
; DI void attn_sample_unit(const Params& p, int u, const bf16_t* Q, const bf16_t* Kb, const bf16_t* Vb, bf16_t* att, LAS float* sl, int lane) {
;     ...
;         else { const float* kp = ck + (((size_t)b * 2048 + idx) * 16 + h) * 64;
; #pragma unroll
;             for (int d4 = 0; d4 < 16; ++d4) { const f32x4 kv = *(const f32x4*)(kp + 4 * d4); const f32x4 qv = *(const LAS f32x4*)(sl + 4 * d4); dot += (kv[0] * qv[0] + kv[1] * qv[1]) + (kv[2] * qv[2] + kv[3] * qv[3]); } }
;         if (valid) { sl[64 + pat * 192 + j] = dot; mx = fmaxf(mx, dot); } }
;     mx = wave_max(mx);
	v_mul_f32_e32 v0, v0, v44
	v_mul_f32_e32 v4, v4, v44
	v_mul_f32_e32 v8, v8, v44
	v_mul_f32_e32 v12, v12, v44
	v_mul_f32_e32 v16, v16, v44
	v_mul_f32_e32 v20, v20, v44
	v_mul_f32_e32 v24, v24, v44
	v_mul_f32_e32 v28, v28, v44
	v_mul_f32_e32 v32, v32, v44
	v_mul_f32_e32 v36, v36, v44
	v_mul_f32_e32 v52, v52, v44
	v_fmac_f32_e32 v0, v1, v45
	v_fmac_f32_e32 v4, v5, v45
	v_fmac_f32_e32 v8, v9, v45
	v_fmac_f32_e32 v12, v13, v45
	v_fmac_f32_e32 v16, v17, v45
	v_fmac_f32_e32 v20, v21, v45
	v_fmac_f32_e32 v24, v25, v45
	v_fmac_f32_e32 v28, v29, v45
	v_fmac_f32_e32 v32, v33, v45
	v_fmac_f32_e32 v36, v37, v45
	v_fmac_f32_e32 v52, v53, v45
	v_fmac_f32_e32 v0, v2, v46
	v_fmac_f32_e32 v4, v6, v46
	v_fmac_f32_e32 v8, v10, v46
	v_fmac_f32_e32 v12, v14, v46
	v_fmac_f32_e32 v16, v18, v46
	v_fmac_f32_e32 v20, v22, v46
	v_fmac_f32_e32 v24, v26, v46
	v_fmac_f32_e32 v28, v30, v46
	v_fmac_f32_e32 v32, v34, v46
	v_fmac_f32_e32 v36, v38, v46
	v_fmac_f32_e32 v52, v54, v46
	v_fmac_f32_e32 v0, v3, v47
	v_fmac_f32_e32 v4, v7, v47
	v_fmac_f32_e32 v8, v11, v47
	v_fmac_f32_e32 v12, v15, v47
	v_fmac_f32_e32 v16, v19, v47
	v_fmac_f32_e32 v20, v23, v47
	v_fmac_f32_e32 v24, v27, v47
	v_fmac_f32_e32 v28, v31, v47
	v_fmac_f32_e32 v32, v35, v47
	v_fmac_f32_e32 v36, v39, v47
	v_fmac_f32_e32 v52, v55, v47
	s_nop 1
	v_add_f32_dpp v0, v0, v0 quad_perm:[1,0,3,2] row_mask:0xf bank_mask:0xf
	v_add_f32_dpp v4, v4, v4 quad_perm:[1,0,3,2] row_mask:0xf bank_mask:0xf
	v_add_f32_dpp v8, v8, v8 quad_perm:[1,0,3,2] row_mask:0xf bank_mask:0xf
	v_add_f32_dpp v12, v12, v12 quad_perm:[1,0,3,2] row_mask:0xf bank_mask:0xf
	v_add_f32_dpp v16, v16, v16 quad_perm:[1,0,3,2] row_mask:0xf bank_mask:0xf
	v_add_f32_dpp v20, v20, v20 quad_perm:[1,0,3,2] row_mask:0xf bank_mask:0xf
	v_add_f32_dpp v24, v24, v24 quad_perm:[1,0,3,2] row_mask:0xf bank_mask:0xf
	v_add_f32_dpp v28, v28, v28 quad_perm:[1,0,3,2] row_mask:0xf bank_mask:0xf
	v_add_f32_dpp v32, v32, v32 quad_perm:[1,0,3,2] row_mask:0xf bank_mask:0xf
	v_add_f32_dpp v36, v36, v36 quad_perm:[1,0,3,2] row_mask:0xf bank_mask:0xf
	v_add_f32_dpp v52, v52, v52 quad_perm:[1,0,3,2] row_mask:0xf bank_mask:0xf
	s_nop 1
	v_add_f32_dpp v0, v0, v0 quad_perm:[2,3,0,1] row_mask:0xf bank_mask:0xf
	v_add_f32_dpp v4, v4, v4 quad_perm:[2,3,0,1] row_mask:0xf bank_mask:0xf
	v_add_f32_dpp v8, v8, v8 quad_perm:[2,3,0,1] row_mask:0xf bank_mask:0xf
	v_add_f32_dpp v12, v12, v12 quad_perm:[2,3,0,1] row_mask:0xf bank_mask:0xf
	v_add_f32_dpp v16, v16, v16 quad_perm:[2,3,0,1] row_mask:0xf bank_mask:0xf
	v_add_f32_dpp v20, v20, v20 quad_perm:[2,3,0,1] row_mask:0xf bank_mask:0xf
	v_add_f32_dpp v24, v24, v24 quad_perm:[2,3,0,1] row_mask:0xf bank_mask:0xf
	v_add_f32_dpp v28, v28, v28 quad_perm:[2,3,0,1] row_mask:0xf bank_mask:0xf
	v_add_f32_dpp v32, v32, v32 quad_perm:[2,3,0,1] row_mask:0xf bank_mask:0xf
	v_add_f32_dpp v36, v36, v36 quad_perm:[2,3,0,1] row_mask:0xf bank_mask:0xf
	v_add_f32_dpp v52, v52, v52 quad_perm:[2,3,0,1] row_mask:0xf bank_mask:0xf
	s_nop 1
	v_add_f32_dpp v0, v0, v0 row_half_mirror row_mask:0xf bank_mask:0xf
	v_add_f32_dpp v4, v4, v4 row_half_mirror row_mask:0xf bank_mask:0xf
	v_add_f32_dpp v8, v8, v8 row_half_mirror row_mask:0xf bank_mask:0xf
	v_add_f32_dpp v12, v12, v12 row_half_mirror row_mask:0xf bank_mask:0xf
	v_add_f32_dpp v16, v16, v16 row_half_mirror row_mask:0xf bank_mask:0xf
	v_add_f32_dpp v20, v20, v20 row_half_mirror row_mask:0xf bank_mask:0xf
	v_add_f32_dpp v24, v24, v24 row_half_mirror row_mask:0xf bank_mask:0xf
	v_add_f32_dpp v28, v28, v28 row_half_mirror row_mask:0xf bank_mask:0xf
	v_add_f32_dpp v32, v32, v32 row_half_mirror row_mask:0xf bank_mask:0xf
	v_add_f32_dpp v36, v36, v36 row_half_mirror row_mask:0xf bank_mask:0xf
	v_add_f32_dpp v52, v52, v52 row_half_mirror row_mask:0xf bank_mask:0xf
	s_nop 1
	v_add_f32_dpp v0, v0, v0 row_mirror row_mask:0xf bank_mask:0xf
	v_add_f32_dpp v4, v4, v4 row_mirror row_mask:0xf bank_mask:0xf
	v_add_f32_dpp v8, v8, v8 row_mirror row_mask:0xf bank_mask:0xf
	v_add_f32_dpp v12, v12, v12 row_mirror row_mask:0xf bank_mask:0xf
	v_add_f32_dpp v16, v16, v16 row_mirror row_mask:0xf bank_mask:0xf
	v_add_f32_dpp v20, v20, v20 row_mirror row_mask:0xf bank_mask:0xf
	v_add_f32_dpp v24, v24, v24 row_mirror row_mask:0xf bank_mask:0xf
	v_add_f32_dpp v28, v28, v28 row_mirror row_mask:0xf bank_mask:0xf
	v_add_f32_dpp v32, v32, v32 row_mirror row_mask:0xf bank_mask:0xf
	v_add_f32_dpp v36, v36, v36 row_mirror row_mask:0xf bank_mask:0xf
	v_add_f32_dpp v52, v52, v52 row_mirror row_mask:0xf bank_mask:0xf
	s_nop 1
	s_mov_b32 s82, 0x10001
	s_mov_b32 s83, 0x10001
	s_mov_b64 exec, s[82:83]
	ds_write_b32 v48, v0 offset:1888
	v_max_f32_e32 v40, v40, v0
	ds_write_b32 v48, v4 offset:1904
	v_max_f32_e32 v40, v40, v4
	ds_write_b32 v48, v8 offset:1920
	v_max_f32_e32 v40, v40, v8
	ds_write_b32 v48, v12 offset:1936
	v_max_f32_e32 v40, v40, v12
	ds_write_b32 v48, v16 offset:1952
	v_max_f32_e32 v40, v40, v16
	ds_write_b32 v48, v20 offset:1968
	v_max_f32_e32 v40, v40, v20
	ds_write_b32 v48, v24 offset:1984
	v_max_f32_e32 v40, v40, v24
	ds_write_b32 v48, v28 offset:2000
	v_max_f32_e32 v40, v40, v28
	ds_write_b32 v48, v32 offset:2016
	v_max_f32_e32 v40, v40, v32
	ds_write_b32 v48, v36 offset:2032
	v_max_f32_e32 v40, v40, v36
	s_mov_b64 exec, 1
	ds_write_b32 v48, v52 offset:2048
	v_max_f32_e32 v40, v40, v52
	s_mov_b64 exec, -1
	s_nop 4
	s_waitcnt vmcnt(0) lgkmcnt(0)

; DI void attn_sample_unit(const Params& p, int u, const bf16_t* Q, const bf16_t* Kb, const bf16_t* Vb, bf16_t* att, LAS float* sl, int lane) {
;     ...
;       for (int pat = 0; pat < 3; ++pat) { const int dil = 1 << (2 * pat);
; #pragma unroll
;         for (int jj = 0; jj < 33; ++jj) { const int j = kg + 4 * jj; int idx = 2048 + t - dil * j; const bool use = (j <= 128) && (idx < 2048);
;             idx = idx < 0 ? 0 : (idx > 2047 ? 2047 : idx); const float pv = use ? sl[64 + pat * 192 + (j > 128 ? 128 : j)] : 0.f;
;             const f32x4 vv = *(const f32x4*)(cv + (((size_t)b * 2048 + idx) * 16 + h) * 64 + 4 * d4);
;             acc += vv * pv; }
.LBB0_1535:
	s_lshl_b32 s86, s5, 1
	v_lshlrev_b32_e32 v0, s86, v147
	s_mul_i32 s0, s5, 0x300
	v_sub_u32_e32 v0, s2, v0
	s_add_i32 s0, s3, s0
	v_cmp_gt_i32_e32 vcc, s81, v0
	s_and_b64 s[78:79], s[8:9], vcc
	v_lshl_add_u32 v217, v147, 2, s0
	v_mov_b32_e32 v132, 0
	s_and_saveexec_b64 s[0:1], s[78:79]
	ds_read_b32 v132, v217 offset:256
	s_or_b64 exec, exec, s[0:1]
	v_med3_i32 v0, v0, 0, v212
	v_lshl_or_b32 v0, v0, 4, s76
	v_mov_b32_e32 v1, s77
	v_lshlrev_b64 v[0:1], 8, v[0:1]
	v_lshl_add_u64 v[0:1], v[134:135], 0, v[0:1]
	global_load_dwordx4 v[0:3], v[0:1], off nt
	v_lshlrev_b32_e32 v4, s86, v149
	v_sub_u32_e32 v4, s2, v4
	v_cmp_gt_i32_e32 vcc, s81, v4
	s_and_b64 s[78:79], s[10:11], vcc
	v_mov_b32_e32 v144, 0
	v_mov_b32_e32 v146, 0
	s_and_saveexec_b64 s[0:1], s[78:79]
	ds_read_b32 v146, v217 offset:272
	s_or_b64 exec, exec, s[0:1]
	v_med3_i32 v4, v4, 0, v212
	v_lshl_or_b32 v4, v4, 4, s76
	v_mov_b32_e32 v5, s77
	v_lshlrev_b64 v[4:5], 8, v[4:5]
	v_lshl_add_u64 v[4:5], v[134:135], 0, v[4:5]
	global_load_dwordx4 v[4:7], v[4:5], off nt
	v_lshlrev_b32_e32 v8, s86, v151
	v_sub_u32_e32 v8, s2, v8
	v_cmp_gt_i32_e32 vcc, s81, v8
	s_and_b64 s[78:79], s[12:13], vcc
	s_and_saveexec_b64 s[0:1], s[78:79]
	ds_read_b32 v144, v217 offset:288
	s_or_b64 exec, exec, s[0:1]
	v_med3_i32 v8, v8, 0, v212
	v_lshl_or_b32 v8, v8, 4, s76
	v_mov_b32_e32 v9, s77
	v_lshlrev_b64 v[8:9], 8, v[8:9]
	v_lshl_add_u64 v[8:9], v[134:135], 0, v[8:9]
	global_load_dwordx4 v[8:11], v[8:9], off nt
	v_lshlrev_b32_e32 v12, s86, v153
	v_sub_u32_e32 v12, s2, v12
	v_cmp_gt_i32_e32 vcc, s81, v12
	s_and_b64 s[78:79], s[14:15], vcc
	v_mov_b32_e32 v148, 0
	v_mov_b32_e32 v150, 0
	s_and_saveexec_b64 s[0:1], s[78:79]
	ds_read_b32 v150, v217 offset:304
	s_or_b64 exec, exec, s[0:1]
	v_med3_i32 v12, v12, 0, v212
	v_lshl_or_b32 v12, v12, 4, s76
	v_mov_b32_e32 v13, s77
	v_lshlrev_b64 v[12:13], 8, v[12:13]
	v_lshl_add_u64 v[12:13], v[134:135], 0, v[12:13]
	global_load_dwordx4 v[12:15], v[12:13], off nt
	v_lshlrev_b32_e32 v16, s86, v155
	v_sub_u32_e32 v16, s2, v16
	v_cmp_gt_i32_e32 vcc, s81, v16
	s_and_b64 s[78:79], s[16:17], vcc
	s_and_saveexec_b64 s[0:1], s[78:79]
	ds_read_b32 v148, v217 offset:320
	s_or_b64 exec, exec, s[0:1]
	v_med3_i32 v16, v16, 0, v212
	v_lshl_or_b32 v16, v16, 4, s76
	v_mov_b32_e32 v17, s77
	v_lshlrev_b64 v[16:17], 8, v[16:17]
	v_lshl_add_u64 v[16:17], v[134:135], 0, v[16:17]
	global_load_dwordx4 v[16:19], v[16:17], off nt
	v_lshlrev_b32_e32 v20, s86, v157
	v_sub_u32_e32 v20, s2, v20
	v_cmp_gt_i32_e32 vcc, s81, v20
	s_and_b64 s[78:79], s[18:19], vcc
	v_mov_b32_e32 v152, 0
	v_mov_b32_e32 v154, 0
	s_and_saveexec_b64 s[0:1], s[78:79]
	ds_read_b32 v154, v217 offset:336
	s_or_b64 exec, exec, s[0:1]
	v_med3_i32 v20, v20, 0, v212
	v_lshl_or_b32 v20, v20, 4, s76
	v_mov_b32_e32 v21, s77
	v_lshlrev_b64 v[20:21], 8, v[20:21]
	v_lshl_add_u64 v[20:21], v[134:135], 0, v[20:21]
	global_load_dwordx4 v[20:23], v[20:21], off nt
	v_lshlrev_b32_e32 v24, s86, v159
	v_sub_u32_e32 v24, s2, v24
	v_cmp_gt_i32_e32 vcc, s81, v24
	s_and_b64 s[78:79], s[20:21], vcc
	s_and_saveexec_b64 s[0:1], s[78:79]
	ds_read_b32 v152, v217 offset:352
	s_or_b64 exec, exec, s[0:1]
	v_med3_i32 v24, v24, 0, v212
	v_lshl_or_b32 v24, v24, 4, s76
	v_mov_b32_e32 v25, s77
	v_lshlrev_b64 v[24:25], 8, v[24:25]
	v_lshl_add_u64 v[24:25], v[134:135], 0, v[24:25]
	global_load_dwordx4 v[24:27], v[24:25], off nt
	v_lshlrev_b32_e32 v28, s86, v161
	v_sub_u32_e32 v28, s2, v28
	v_cmp_gt_i32_e32 vcc, s81, v28
	s_and_b64 s[78:79], s[22:23], vcc
	v_mov_b32_e32 v156, 0
	v_mov_b32_e32 v158, 0
	s_and_saveexec_b64 s[0:1], s[78:79]
	ds_read_b32 v158, v217 offset:368
	s_or_b64 exec, exec, s[0:1]
	v_med3_i32 v28, v28, 0, v212
	v_lshl_or_b32 v28, v28, 4, s76
	v_mov_b32_e32 v29, s77
	v_lshlrev_b64 v[28:29], 8, v[28:29]
	v_lshl_add_u64 v[28:29], v[134:135], 0, v[28:29]
	global_load_dwordx4 v[28:31], v[28:29], off nt
	v_lshlrev_b32_e32 v32, s86, v163
	v_sub_u32_e32 v32, s2, v32
	v_cmp_gt_i32_e32 vcc, s81, v32
	s_and_b64 s[78:79], s[24:25], vcc
	s_and_saveexec_b64 s[0:1], s[78:79]
	ds_read_b32 v156, v217 offset:384
	s_or_b64 exec, exec, s[0:1]
	v_med3_i32 v32, v32, 0, v212
	v_lshl_or_b32 v32, v32, 4, s76
	v_mov_b32_e32 v33, s77
	v_lshlrev_b64 v[32:33], 8, v[32:33]
	v_lshl_add_u64 v[32:33], v[134:135], 0, v[32:33]
	global_load_dwordx4 v[32:35], v[32:33], off nt
	v_lshlrev_b32_e32 v36, s86, v165
	v_sub_u32_e32 v36, s2, v36
	v_cmp_gt_i32_e32 vcc, s81, v36
	s_and_b64 s[78:79], s[26:27], vcc
	v_mov_b32_e32 v162, 0
	v_mov_b32_e32 v164, 0
	s_and_saveexec_b64 s[0:1], s[78:79]
	ds_read_b32 v164, v217 offset:400
	s_or_b64 exec, exec, s[0:1]
	v_med3_i32 v36, v36, 0, v212
	v_lshl_or_b32 v36, v36, 4, s76
	v_mov_b32_e32 v37, s77
	v_lshlrev_b64 v[36:37], 8, v[36:37]
	v_lshl_add_u64 v[36:37], v[134:135], 0, v[36:37]
	global_load_dwordx4 v[36:39], v[36:37], off nt
	v_lshlrev_b32_e32 v40, s86, v167
	v_sub_u32_e32 v40, s2, v40
	v_cmp_gt_i32_e32 vcc, s81, v40
	s_and_b64 s[78:79], s[28:29], vcc
	s_and_saveexec_b64 s[0:1], s[78:79]
	ds_read_b32 v162, v217 offset:416
	s_or_b64 exec, exec, s[0:1]
	v_med3_i32 v40, v40, 0, v212
	v_lshl_or_b32 v40, v40, 4, s76
	v_mov_b32_e32 v41, s77
	v_lshlrev_b64 v[40:41], 8, v[40:41]
	v_lshl_add_u64 v[40:41], v[134:135], 0, v[40:41]
	global_load_dwordx4 v[40:43], v[40:41], off nt
	v_lshlrev_b32_e32 v44, s86, v169
	v_sub_u32_e32 v44, s2, v44
	v_cmp_gt_i32_e32 vcc, s81, v44
	s_and_b64 s[78:79], s[30:31], vcc
	v_mov_b32_e32 v166, 0
	v_mov_b32_e32 v168, 0
	s_and_saveexec_b64 s[0:1], s[78:79]
	ds_read_b32 v168, v217 offset:432
	s_or_b64 exec, exec, s[0:1]
	v_med3_i32 v44, v44, 0, v212
	v_lshl_or_b32 v44, v44, 4, s76
	v_mov_b32_e32 v45, s77
; DI void attn_sample_unit(const Params& p, int u, const bf16_t* Q, const bf16_t* Kb, const bf16_t* Vb, bf16_t* att, LAS float* sl, int lane) {
;     ...
;       for (int pat = 0; pat < 3; ++pat) { const int dil = 1 << (2 * pat);
; #pragma unroll
;         for (int jj = 0; jj < 33; ++jj) { const int j = kg + 4 * jj; int idx = 2048 + t - dil * j; const bool use = (j <= 128) && (idx < 2048);
;             idx = idx < 0 ? 0 : (idx > 2047 ? 2047 : idx); const float pv = use ? sl[64 + pat * 192 + (j > 128 ? 128 : j)] : 0.f;
;             const f32x4 vv = *(const f32x4*)(cv + (((size_t)b * 2048 + idx) * 16 + h) * 64 + 4 * d4);
;             acc += vv * pv; }
	v_lshlrev_b64 v[44:45], 8, v[44:45]
	v_lshl_add_u64 v[44:45], v[134:135], 0, v[44:45]
	global_load_dwordx4 v[44:47], v[44:45], off nt
	v_lshlrev_b32_e32 v48, s86, v171
	v_sub_u32_e32 v48, s2, v48
	v_cmp_gt_i32_e32 vcc, s81, v48
	s_and_b64 s[78:79], s[34:35], vcc
	s_and_saveexec_b64 s[0:1], s[78:79]
	ds_read_b32 v166, v217 offset:448
	s_or_b64 exec, exec, s[0:1]
	v_med3_i32 v48, v48, 0, v212
	v_lshl_or_b32 v48, v48, 4, s76
	v_mov_b32_e32 v49, s77
	v_lshlrev_b64 v[48:49], 8, v[48:49]
	v_lshl_add_u64 v[48:49], v[134:135], 0, v[48:49]
	global_load_dwordx4 v[48:51], v[48:49], off nt
	v_lshlrev_b32_e32 v52, s86, v173
	v_sub_u32_e32 v52, s2, v52
	v_cmp_gt_i32_e32 vcc, s81, v52
	s_and_b64 s[78:79], s[36:37], vcc
	v_mov_b32_e32 v170, 0
	v_mov_b32_e32 v172, 0
	s_and_saveexec_b64 s[0:1], s[78:79]
	ds_read_b32 v172, v217 offset:464
	s_or_b64 exec, exec, s[0:1]
	v_med3_i32 v52, v52, 0, v212
	v_lshl_or_b32 v52, v52, 4, s76
	v_mov_b32_e32 v53, s77
	v_lshlrev_b64 v[52:53], 8, v[52:53]
	v_lshl_add_u64 v[52:53], v[134:135], 0, v[52:53]
	global_load_dwordx4 v[52:55], v[52:53], off nt
	v_lshlrev_b32_e32 v56, s86, v175
	v_sub_u32_e32 v56, s2, v56
	v_cmp_gt_i32_e32 vcc, s81, v56
	s_and_b64 s[78:79], s[38:39], vcc
	s_and_saveexec_b64 s[0:1], s[78:79]
	ds_read_b32 v170, v217 offset:480
	s_or_b64 exec, exec, s[0:1]
	v_med3_i32 v56, v56, 0, v212
	v_lshl_or_b32 v56, v56, 4, s76
	v_mov_b32_e32 v57, s77
	v_lshlrev_b64 v[56:57], 8, v[56:57]
	v_lshl_add_u64 v[56:57], v[134:135], 0, v[56:57]
	global_load_dwordx4 v[56:59], v[56:57], off nt
	v_lshlrev_b32_e32 v60, s86, v177
	v_sub_u32_e32 v60, s2, v60
	v_cmp_gt_i32_e32 vcc, s81, v60
	s_and_b64 s[78:79], s[40:41], vcc
	v_mov_b32_e32 v174, 0
	v_mov_b32_e32 v176, 0
	s_and_saveexec_b64 s[0:1], s[78:79]
	ds_read_b32 v176, v217 offset:496
	s_or_b64 exec, exec, s[0:1]
	v_med3_i32 v60, v60, 0, v212
	v_lshl_or_b32 v60, v60, 4, s76
	v_mov_b32_e32 v61, s77
	v_lshlrev_b64 v[60:61], 8, v[60:61]
	v_lshl_add_u64 v[60:61], v[134:135], 0, v[60:61]
	global_load_dwordx4 v[60:63], v[60:61], off nt
	v_lshlrev_b32_e32 v64, s86, v179
	v_sub_u32_e32 v64, s2, v64
	v_cmp_gt_i32_e32 vcc, s81, v64
	s_and_b64 s[78:79], s[42:43], vcc
	s_and_saveexec_b64 s[0:1], s[78:79]
	ds_read_b32 v174, v217 offset:512
	s_or_b64 exec, exec, s[0:1]
	v_med3_i32 v64, v64, 0, v212
	v_lshl_or_b32 v64, v64, 4, s76
	v_mov_b32_e32 v65, s77
	v_lshlrev_b64 v[64:65], 8, v[64:65]
	v_lshl_add_u64 v[64:65], v[134:135], 0, v[64:65]
	global_load_dwordx4 v[64:67], v[64:65], off nt
	v_lshlrev_b32_e32 v68, s86, v181
	v_sub_u32_e32 v68, s2, v68
	v_cmp_gt_i32_e32 vcc, s81, v68
	s_and_b64 s[78:79], s[44:45], vcc
	v_mov_b32_e32 v178, 0
	v_mov_b32_e32 v180, 0
	s_and_saveexec_b64 s[0:1], s[78:79]
	ds_read_b32 v180, v217 offset:528
	s_or_b64 exec, exec, s[0:1]
	v_med3_i32 v68, v68, 0, v212
	v_lshl_or_b32 v68, v68, 4, s76
	v_mov_b32_e32 v69, s77
	v_lshlrev_b64 v[68:69], 8, v[68:69]
	v_lshl_add_u64 v[68:69], v[134:135], 0, v[68:69]
	global_load_dwordx4 v[68:71], v[68:69], off nt
	v_lshlrev_b32_e32 v72, s86, v183
	v_sub_u32_e32 v72, s2, v72
	v_cmp_gt_i32_e32 vcc, s81, v72
	s_and_b64 s[78:79], s[46:47], vcc
	s_and_saveexec_b64 s[0:1], s[78:79]
	ds_read_b32 v178, v217 offset:544
	s_or_b64 exec, exec, s[0:1]
	v_med3_i32 v72, v72, 0, v212
	v_lshl_or_b32 v72, v72, 4, s76
	v_mov_b32_e32 v73, s77
	v_lshlrev_b64 v[72:73], 8, v[72:73]
	v_lshl_add_u64 v[72:73], v[134:135], 0, v[72:73]
	global_load_dwordx4 v[72:75], v[72:73], off nt
	v_lshlrev_b32_e32 v76, s86, v185
	v_sub_u32_e32 v76, s2, v76
	v_cmp_gt_i32_e32 vcc, s81, v76
	s_and_b64 s[78:79], s[48:49], vcc
	v_mov_b32_e32 v182, 0
	v_mov_b32_e32 v184, 0
	s_and_saveexec_b64 s[0:1], s[78:79]
	ds_read_b32 v184, v217 offset:560
	s_or_b64 exec, exec, s[0:1]
	v_med3_i32 v76, v76, 0, v212
	v_lshl_or_b32 v76, v76, 4, s76
	v_mov_b32_e32 v77, s77
	v_lshlrev_b64 v[76:77], 8, v[76:77]
	v_lshl_add_u64 v[76:77], v[134:135], 0, v[76:77]
	global_load_dwordx4 v[76:79], v[76:77], off nt
	v_lshlrev_b32_e32 v80, s86, v187
	v_sub_u32_e32 v80, s2, v80
	v_cmp_gt_i32_e32 vcc, s81, v80
	s_and_b64 s[78:79], s[50:51], vcc
	s_and_saveexec_b64 s[0:1], s[78:79]
	ds_read_b32 v182, v217 offset:576
	s_or_b64 exec, exec, s[0:1]
	v_med3_i32 v80, v80, 0, v212
	v_lshl_or_b32 v80, v80, 4, s76
	v_mov_b32_e32 v81, s77
	v_lshlrev_b64 v[80:81], 8, v[80:81]
	v_lshl_add_u64 v[80:81], v[134:135], 0, v[80:81]
	global_load_dwordx4 v[80:83], v[80:81], off nt
	v_lshlrev_b32_e32 v84, s86, v189
	v_sub_u32_e32 v84, s2, v84
	v_cmp_gt_i32_e32 vcc, s81, v84
	s_and_b64 s[78:79], s[52:53], vcc
	v_mov_b32_e32 v186, 0
	v_mov_b32_e32 v188, 0
	s_and_saveexec_b64 s[0:1], s[78:79]
	ds_read_b32 v188, v217 offset:592
	s_or_b64 exec, exec, s[0:1]
	v_med3_i32 v84, v84, 0, v212
	v_lshl_or_b32 v84, v84, 4, s76
	v_mov_b32_e32 v85, s77
	v_lshlrev_b64 v[84:85], 8, v[84:85]
	v_lshl_add_u64 v[84:85], v[134:135], 0, v[84:85]
	global_load_dwordx4 v[84:87], v[84:85], off nt
	v_lshlrev_b32_e32 v88, s86, v191
	v_sub_u32_e32 v88, s2, v88
	v_cmp_gt_i32_e32 vcc, s81, v88
	s_and_b64 s[78:79], s[54:55], vcc
	s_and_saveexec_b64 s[0:1], s[78:79]
	ds_read_b32 v186, v217 offset:608
	s_or_b64 exec, exec, s[0:1]
	v_med3_i32 v88, v88, 0, v212
	v_lshl_or_b32 v88, v88, 4, s76
	v_mov_b32_e32 v89, s77
	v_lshlrev_b64 v[88:89], 8, v[88:89]
	v_lshl_add_u64 v[88:89], v[134:135], 0, v[88:89]
	global_load_dwordx4 v[88:91], v[88:89], off nt
	v_lshlrev_b32_e32 v92, s86, v193
	v_sub_u32_e32 v92, s2, v92
	v_cmp_gt_i32_e32 vcc, s81, v92
	s_and_b64 s[78:79], s[56:57], vcc
	v_mov_b32_e32 v190, 0
	v_mov_b32_e32 v192, 0
	s_and_saveexec_b64 s[0:1], s[78:79]
	ds_read_b32 v192, v217 offset:624
	s_or_b64 exec, exec, s[0:1]
	v_med3_i32 v92, v92, 0, v212
; DI void attn_sample_unit(const Params& p, int u, const bf16_t* Q, const bf16_t* Kb, const bf16_t* Vb, bf16_t* att, LAS float* sl, int lane) {
;     ...
;       for (int pat = 0; pat < 3; ++pat) { const int dil = 1 << (2 * pat);
; #pragma unroll
;         for (int jj = 0; jj < 33; ++jj) { const int j = kg + 4 * jj; int idx = 2048 + t - dil * j; const bool use = (j <= 128) && (idx < 2048);
;             idx = idx < 0 ? 0 : (idx > 2047 ? 2047 : idx); const float pv = use ? sl[64 + pat * 192 + (j > 128 ? 128 : j)] : 0.f;
;             const f32x4 vv = *(const f32x4*)(cv + (((size_t)b * 2048 + idx) * 16 + h) * 64 + 4 * d4);
;             acc += vv * pv; }
	v_lshl_or_b32 v92, v92, 4, s76
	v_mov_b32_e32 v93, s77
	v_lshlrev_b64 v[92:93], 8, v[92:93]
	v_lshl_add_u64 v[92:93], v[134:135], 0, v[92:93]
	global_load_dwordx4 v[92:95], v[92:93], off nt
	v_lshlrev_b32_e32 v96, s86, v195
	v_sub_u32_e32 v96, s2, v96
	v_cmp_gt_i32_e32 vcc, s81, v96
	s_and_b64 s[78:79], s[58:59], vcc
	s_and_saveexec_b64 s[0:1], s[78:79]
	ds_read_b32 v190, v217 offset:640
	s_or_b64 exec, exec, s[0:1]
	v_med3_i32 v96, v96, 0, v212
	v_lshl_or_b32 v96, v96, 4, s76
	v_mov_b32_e32 v97, s77
	v_lshlrev_b64 v[96:97], 8, v[96:97]
	v_lshl_add_u64 v[96:97], v[134:135], 0, v[96:97]
	global_load_dwordx4 v[96:99], v[96:97], off nt
	v_lshlrev_b32_e32 v100, s86, v197
	v_sub_u32_e32 v100, s2, v100
	v_cmp_gt_i32_e32 vcc, s81, v100
	s_and_b64 s[78:79], s[60:61], vcc
	v_mov_b32_e32 v194, 0
	v_mov_b32_e32 v196, 0
	s_and_saveexec_b64 s[0:1], s[78:79]
	ds_read_b32 v196, v217 offset:656
	s_or_b64 exec, exec, s[0:1]
	v_med3_i32 v100, v100, 0, v212
	v_lshl_or_b32 v100, v100, 4, s76
	v_mov_b32_e32 v101, s77
	v_lshlrev_b64 v[100:101], 8, v[100:101]
	v_lshl_add_u64 v[100:101], v[134:135], 0, v[100:101]
	global_load_dwordx4 v[100:103], v[100:101], off nt
	v_lshlrev_b32_e32 v104, s86, v199
	v_sub_u32_e32 v104, s2, v104
	v_cmp_gt_i32_e32 vcc, s81, v104
	s_and_b64 s[78:79], s[62:63], vcc
	s_and_saveexec_b64 s[0:1], s[78:79]
	ds_read_b32 v194, v217 offset:672
	s_or_b64 exec, exec, s[0:1]
	v_med3_i32 v104, v104, 0, v212
	v_lshl_or_b32 v104, v104, 4, s76
	v_mov_b32_e32 v105, s77
	v_lshlrev_b64 v[104:105], 8, v[104:105]
	v_lshl_add_u64 v[104:105], v[134:135], 0, v[104:105]
	global_load_dwordx4 v[104:107], v[104:105], off nt
	v_lshlrev_b32_e32 v108, s86, v201
	v_sub_u32_e32 v108, s2, v108
	v_cmp_gt_i32_e32 vcc, s81, v108
	s_and_b64 s[78:79], s[64:65], vcc
	v_mov_b32_e32 v198, 0
	v_mov_b32_e32 v200, 0
	s_and_saveexec_b64 s[0:1], s[78:79]
	ds_read_b32 v200, v217 offset:688
	s_or_b64 exec, exec, s[0:1]
	v_med3_i32 v108, v108, 0, v212
	v_lshl_or_b32 v108, v108, 4, s76
	v_mov_b32_e32 v109, s77
	v_lshlrev_b64 v[108:109], 8, v[108:109]
	v_lshl_add_u64 v[108:109], v[134:135], 0, v[108:109]
	global_load_dwordx4 v[108:111], v[108:109], off nt
	v_lshlrev_b32_e32 v112, s86, v203
	v_sub_u32_e32 v112, s2, v112
	v_cmp_gt_i32_e32 vcc, s81, v112
	s_and_b64 s[78:79], s[66:67], vcc
	s_and_saveexec_b64 s[0:1], s[78:79]
	ds_read_b32 v198, v217 offset:704
	s_or_b64 exec, exec, s[0:1]
	v_med3_i32 v112, v112, 0, v212
	v_lshl_or_b32 v112, v112, 4, s76
	v_mov_b32_e32 v113, s77
	v_lshlrev_b64 v[112:113], 8, v[112:113]
	v_lshl_add_u64 v[112:113], v[134:135], 0, v[112:113]
	global_load_dwordx4 v[112:115], v[112:113], off nt
	v_lshlrev_b32_e32 v116, s86, v205
	v_sub_u32_e32 v116, s2, v116
	v_cmp_gt_i32_e32 vcc, s81, v116
	s_and_b64 s[78:79], s[68:69], vcc
	v_mov_b32_e32 v202, 0
	v_mov_b32_e32 v204, 0
	s_and_saveexec_b64 s[0:1], s[78:79]
	ds_read_b32 v204, v217 offset:720
	s_or_b64 exec, exec, s[0:1]
	v_med3_i32 v116, v116, 0, v212
	v_lshl_or_b32 v116, v116, 4, s76
	v_mov_b32_e32 v117, s77
	v_lshlrev_b64 v[116:117], 8, v[116:117]
	v_lshl_add_u64 v[116:117], v[134:135], 0, v[116:117]
	global_load_dwordx4 v[116:119], v[116:117], off nt
	v_lshlrev_b32_e32 v120, s86, v207
	v_sub_u32_e32 v120, s2, v120
	v_cmp_gt_i32_e32 vcc, s81, v120
	s_and_b64 s[78:79], s[70:71], vcc
	s_and_saveexec_b64 s[0:1], s[78:79]
	ds_read_b32 v202, v217 offset:736
	s_or_b64 exec, exec, s[0:1]
	v_med3_i32 v120, v120, 0, v212
	v_lshl_or_b32 v120, v120, 4, s76
	v_mov_b32_e32 v121, s77
	v_lshlrev_b64 v[120:121], 8, v[120:121]
	v_lshl_add_u64 v[120:121], v[134:135], 0, v[120:121]
	global_load_dwordx4 v[120:123], v[120:121], off nt
	v_lshlrev_b32_e32 v124, s86, v208
	v_sub_u32_e32 v124, s2, v124
	v_cmp_gt_i32_e32 vcc, s81, v124
	s_and_b64 s[78:79], s[72:73], vcc
	v_mov_b32_e32 v160, 0
	v_mov_b32_e32 v206, 0
	s_and_saveexec_b64 s[0:1], s[78:79]
	ds_read_b32 v206, v217 offset:752
	s_or_b64 exec, exec, s[0:1]
	v_med3_i32 v124, v124, 0, v212
	v_lshl_or_b32 v124, v124, 4, s76
	v_mov_b32_e32 v125, s77
	v_lshlrev_b64 v[124:125], 8, v[124:125]
	v_lshl_add_u64 v[124:125], v[134:135], 0, v[124:125]
	global_load_dwordx4 v[124:127], v[124:125], off nt
	v_lshlrev_b32_e32 v218, s86, v209
	v_sub_u32_e32 v218, s2, v218
	v_med3_i32 v220, v218, 0, v212
	v_lshl_or_b32 v220, v220, 4, s76
	v_mov_b32_e32 v221, s77
	v_lshlrev_b64 v[220:221], 8, v[220:221]
	v_lshl_add_u64 v[220:221], v[134:135], 0, v[220:221]
	global_load_dwordx4 v[224:227], v[220:221], off nt
	v_cmp_gt_i32_e32 vcc, s81, v218
	s_and_b64 s[78:79], s[74:75], vcc
	s_and_saveexec_b64 s[0:1], s[78:79]
	ds_read_b32 v160, v217 offset:768
	s_or_b64 exec, exec, s[0:1]
	s_waitcnt vmcnt(32) lgkmcnt(0)
	v_pk_fma_f32 v[2:3], v[2:3], v[132:133], v[142:143] op_sel_hi:[1,0,1]
	v_pk_fma_f32 v[0:1], v[0:1], v[132:133], v[140:141] op_sel_hi:[1,0,1]
	s_waitcnt vmcnt(31)
	v_pk_fma_f32 v[2:3], v[6:7], v[146:147], v[2:3] op_sel_hi:[1,0,1]
	v_pk_fma_f32 v[0:1], v[4:5], v[146:147], v[0:1] op_sel_hi:[1,0,1]
	s_waitcnt vmcnt(30)
; DI void attn_sample_unit(const Params& p, int u, const bf16_t* Q, const bf16_t* Kb, const bf16_t* Vb, bf16_t* att, LAS float* sl, int lane) {
;     ...
;             acc += vv * pv; }
;         if (kg == 0) { for (int j = 0; dil * j <= t; ++j) { const int idx = 2048 + t - dil * j; const float pv = sl[64 + pat * 192 + j];
	v_pk_fma_f32 v[2:3], v[10:11], v[144:145], v[2:3] op_sel_hi:[1,0,1]
	v_pk_fma_f32 v[0:1], v[8:9], v[144:145], v[0:1] op_sel_hi:[1,0,1]
	s_waitcnt vmcnt(29)
	v_pk_fma_f32 v[2:3], v[14:15], v[150:151], v[2:3] op_sel_hi:[1,0,1]
	v_pk_fma_f32 v[0:1], v[12:13], v[150:151], v[0:1] op_sel_hi:[1,0,1]
	s_waitcnt vmcnt(28)
	v_pk_fma_f32 v[2:3], v[18:19], v[148:149], v[2:3] op_sel_hi:[1,0,1]
	v_pk_fma_f32 v[0:1], v[16:17], v[148:149], v[0:1] op_sel_hi:[1,0,1]
	s_waitcnt vmcnt(27)
	v_pk_fma_f32 v[2:3], v[22:23], v[154:155], v[2:3] op_sel_hi:[1,0,1]
	v_pk_fma_f32 v[0:1], v[20:21], v[154:155], v[0:1] op_sel_hi:[1,0,1]
	s_waitcnt vmcnt(26)
	v_pk_fma_f32 v[2:3], v[26:27], v[152:153], v[2:3] op_sel_hi:[1,0,1]
	v_pk_fma_f32 v[0:1], v[24:25], v[152:153], v[0:1] op_sel_hi:[1,0,1]
	s_waitcnt vmcnt(25)
	v_pk_fma_f32 v[2:3], v[30:31], v[158:159], v[2:3] op_sel_hi:[1,0,1]
	v_pk_fma_f32 v[0:1], v[28:29], v[158:159], v[0:1] op_sel_hi:[1,0,1]
	s_waitcnt vmcnt(24)
	v_pk_fma_f32 v[2:3], v[34:35], v[156:157], v[2:3] op_sel_hi:[1,0,1]
	v_pk_fma_f32 v[0:1], v[32:33], v[156:157], v[0:1] op_sel_hi:[1,0,1]
	s_waitcnt vmcnt(23)
	v_pk_fma_f32 v[2:3], v[38:39], v[164:165], v[2:3] op_sel_hi:[1,0,1]
	v_pk_fma_f32 v[0:1], v[36:37], v[164:165], v[0:1] op_sel_hi:[1,0,1]
	s_waitcnt vmcnt(22)
	v_pk_fma_f32 v[2:3], v[42:43], v[162:163], v[2:3] op_sel_hi:[1,0,1]
	v_pk_fma_f32 v[0:1], v[40:41], v[162:163], v[0:1] op_sel_hi:[1,0,1]
	s_waitcnt vmcnt(21)
	v_pk_fma_f32 v[2:3], v[46:47], v[168:169], v[2:3] op_sel_hi:[1,0,1]
	v_pk_fma_f32 v[0:1], v[44:45], v[168:169], v[0:1] op_sel_hi:[1,0,1]
	s_waitcnt vmcnt(20)
	v_pk_fma_f32 v[2:3], v[50:51], v[166:167], v[2:3] op_sel_hi:[1,0,1]
	v_pk_fma_f32 v[0:1], v[48:49], v[166:167], v[0:1] op_sel_hi:[1,0,1]
	s_waitcnt vmcnt(19)
	v_pk_fma_f32 v[2:3], v[54:55], v[172:173], v[2:3] op_sel_hi:[1,0,1]
	v_pk_fma_f32 v[0:1], v[52:53], v[172:173], v[0:1] op_sel_hi:[1,0,1]
	s_waitcnt vmcnt(18)
	v_pk_fma_f32 v[2:3], v[58:59], v[170:171], v[2:3] op_sel_hi:[1,0,1]
	v_pk_fma_f32 v[0:1], v[56:57], v[170:171], v[0:1] op_sel_hi:[1,0,1]
	s_waitcnt vmcnt(17)
	v_pk_fma_f32 v[2:3], v[62:63], v[176:177], v[2:3] op_sel_hi:[1,0,1]
	v_pk_fma_f32 v[0:1], v[60:61], v[176:177], v[0:1] op_sel_hi:[1,0,1]
	s_waitcnt vmcnt(16)
	v_pk_fma_f32 v[2:3], v[66:67], v[174:175], v[2:3] op_sel_hi:[1,0,1]
	v_pk_fma_f32 v[0:1], v[64:65], v[174:175], v[0:1] op_sel_hi:[1,0,1]
	s_waitcnt vmcnt(15)
	v_pk_fma_f32 v[2:3], v[70:71], v[180:181], v[2:3] op_sel_hi:[1,0,1]
	v_pk_fma_f32 v[0:1], v[68:69], v[180:181], v[0:1] op_sel_hi:[1,0,1]
	s_waitcnt vmcnt(14)
	v_pk_fma_f32 v[2:3], v[74:75], v[178:179], v[2:3] op_sel_hi:[1,0,1]
	v_pk_fma_f32 v[0:1], v[72:73], v[178:179], v[0:1] op_sel_hi:[1,0,1]
	s_waitcnt vmcnt(13)
	v_pk_fma_f32 v[2:3], v[78:79], v[184:185], v[2:3] op_sel_hi:[1,0,1]
	v_pk_fma_f32 v[0:1], v[76:77], v[184:185], v[0:1] op_sel_hi:[1,0,1]
	s_waitcnt vmcnt(12)
	v_pk_fma_f32 v[2:3], v[82:83], v[182:183], v[2:3] op_sel_hi:[1,0,1]
	v_pk_fma_f32 v[0:1], v[80:81], v[182:183], v[0:1] op_sel_hi:[1,0,1]
	s_waitcnt vmcnt(11)
	v_pk_fma_f32 v[2:3], v[86:87], v[188:189], v[2:3] op_sel_hi:[1,0,1]
	v_pk_fma_f32 v[0:1], v[84:85], v[188:189], v[0:1] op_sel_hi:[1,0,1]
	s_waitcnt vmcnt(10)
	v_pk_fma_f32 v[2:3], v[90:91], v[186:187], v[2:3] op_sel_hi:[1,0,1]
	v_pk_fma_f32 v[0:1], v[88:89], v[186:187], v[0:1] op_sel_hi:[1,0,1]
	s_waitcnt vmcnt(9)
	v_pk_fma_f32 v[2:3], v[94:95], v[192:193], v[2:3] op_sel_hi:[1,0,1]
	v_pk_fma_f32 v[0:1], v[92:93], v[192:193], v[0:1] op_sel_hi:[1,0,1]
	s_waitcnt vmcnt(8)
	v_pk_fma_f32 v[2:3], v[98:99], v[190:191], v[2:3] op_sel_hi:[1,0,1]
	v_pk_fma_f32 v[0:1], v[96:97], v[190:191], v[0:1] op_sel_hi:[1,0,1]
	s_waitcnt vmcnt(7)
	v_pk_fma_f32 v[2:3], v[102:103], v[196:197], v[2:3] op_sel_hi:[1,0,1]
	v_pk_fma_f32 v[0:1], v[100:101], v[196:197], v[0:1] op_sel_hi:[1,0,1]
	s_waitcnt vmcnt(6)
	v_pk_fma_f32 v[2:3], v[106:107], v[194:195], v[2:3] op_sel_hi:[1,0,1]
	v_pk_fma_f32 v[0:1], v[104:105], v[194:195], v[0:1] op_sel_hi:[1,0,1]
	s_waitcnt vmcnt(5)
	v_pk_fma_f32 v[2:3], v[110:111], v[200:201], v[2:3] op_sel_hi:[1,0,1]
	v_pk_fma_f32 v[0:1], v[108:109], v[200:201], v[0:1] op_sel_hi:[1,0,1]
	s_waitcnt vmcnt(4)
	v_pk_fma_f32 v[2:3], v[114:115], v[198:199], v[2:3] op_sel_hi:[1,0,1]
	v_pk_fma_f32 v[0:1], v[112:113], v[198:199], v[0:1] op_sel_hi:[1,0,1]
	s_waitcnt vmcnt(3)
	v_pk_fma_f32 v[2:3], v[118:119], v[204:205], v[2:3] op_sel_hi:[1,0,1]
	v_pk_fma_f32 v[0:1], v[116:117], v[204:205], v[0:1] op_sel_hi:[1,0,1]
	s_waitcnt vmcnt(2)
	v_pk_fma_f32 v[2:3], v[122:123], v[202:203], v[2:3] op_sel_hi:[1,0,1]
	v_pk_fma_f32 v[4:5], v[120:121], v[202:203], v[0:1] op_sel_hi:[1,0,1]
	s_waitcnt vmcnt(1)
	v_pk_fma_f32 v[0:1], v[126:127], v[206:207], v[2:3] op_sel_hi:[1,0,1]
	v_pk_fma_f32 v[2:3], v[124:125], v[206:207], v[4:5] op_sel_hi:[1,0,1]
	s_waitcnt vmcnt(0)
	v_pk_fma_f32 v[142:143], v[226:227], v[160:161], v[0:1] op_sel_hi:[1,0,1]
	v_pk_fma_f32 v[140:141], v[224:225], v[160:161], v[2:3] op_sel_hi:[1,0,1]
	s_and_saveexec_b64 s[0:1], s[6:7]
	s_cbranch_execz .LBB0_1534
	s_mov_b32 s89, 0
	s_mov_b32 s87, 1
	s_mov_b32 s88, s85
